# attention: K/V LDS-DMA issue for the next tile moved from tile boundary into the QK^T MFMA stream (start-of-tile wait is now vmcnt(0)); plus earlier FFN-up DMA rebalance and QK read pipelining
# speedup vs baseline: 1.0057x; 1.0045x over previous
.LBB0_562:
	v_add_f32_e32 v130, v247, v248
	v_fmac_f32_e32 v130, v237, v246
	v_add_f32_e32 v237, v146, v147
	s_add_i32 s97, s97, 2
	v_fmac_f32_e32 v237, v130, v250
	v_lshl_add_u64 v[216:217], v[216:217], 0, s[46:47]
	s_cmp_ge_u32 s14, s17
	v_lshl_add_u64 v[218:219], v[218:219], 0, s[46:47]
	s_cbranch_scc1 .LBB0_581
.LBB0_563:
	s_waitcnt vmcnt(0)
.LBB0_567:
	s_barrier
	ds_read_b128 v[194:197], v238
	ds_read_b128 v[198:201], v239
	ds_read_b128 v[202:205], v238 offset:8192
	ds_read_b128 v[206:209], v239 offset:8192
	s_waitcnt lgkmcnt(3)
	v_mfma_f32_32x32x16_bf16 v[146:161], v[194:197], v[162:165], 0
	ds_read_b128 v[194:197], v240
	s_waitcnt lgkmcnt(3)
	v_mfma_f32_32x32x16_bf16 v[146:161], v[198:201], v[166:169], v[146:161]
	s_cmp_lt_u32 s97, 5
	s_cbranch_scc1 .Lad1a_0
	s_mov_b64 s[100:101], 0xc0000
	s_mov_b32 m0, s77
	v_lshl_add_u64 v[250:251], v[222:223], 0, s[100:101]
	global_load_lds_dwordx4 v[250:251], off
.Lad1a_0:
	ds_read_b128 v[198:201], v240 offset:8192
	s_waitcnt lgkmcnt(3)
	v_mfma_f32_32x32x16_bf16 v[130:145], v[202:205], v[162:165], 0
	ds_read_b128 v[202:205], v241
	s_waitcnt lgkmcnt(3)
	v_mfma_f32_32x32x16_bf16 v[130:145], v[206:209], v[166:169], v[130:145]
	s_cmp_lt_u32 s97, 5
	s_cbranch_scc1 .Lad1a_1
	s_mov_b64 s[100:101], 0xe0000
	s_mov_b32 m0, s89
	v_lshl_add_u64 v[250:251], v[222:223], 0, s[100:101]
	global_load_lds_dwordx4 v[250:251], off
.Lad1a_1:
	ds_read_b128 v[206:209], v241 offset:8192
	s_waitcnt lgkmcnt(3)
	v_mfma_f32_32x32x16_bf16 v[146:161], v[194:197], v[170:173], v[146:161]
	ds_read_b128 v[194:197], v242
	s_waitcnt lgkmcnt(3)
	v_mfma_f32_32x32x16_bf16 v[130:145], v[198:201], v[170:173], v[130:145]
	s_cmp_lt_u32 s97, 5
	s_cbranch_scc1 .Lad1a_2
	s_mov_b64 s[100:101], 0xc0000
	s_add_i32 m0, s67, 0x10000
	v_lshl_add_u64 v[250:251], v[220:221], 0, s[100:101]
	global_load_lds_dwordx4 v[250:251], off
.Lad1a_2:
	ds_read_b128 v[198:201], v242 offset:8192
	s_waitcnt lgkmcnt(3)
	v_mfma_f32_32x32x16_bf16 v[146:161], v[202:205], v[174:177], v[146:161]
	ds_read_b128 v[202:205], v243
	s_waitcnt lgkmcnt(3)
	v_mfma_f32_32x32x16_bf16 v[130:145], v[206:209], v[174:177], v[130:145]
	s_cmp_lt_u32 s97, 5
	s_cbranch_scc1 .Lad1a_3
	s_mov_b64 s[100:101], 0xe0000
	s_add_i32 m0, s67, 0x12000
	v_lshl_add_u64 v[250:251], v[220:221], 0, s[100:101]
	global_load_lds_dwordx4 v[250:251], off
.Lad1a_3:
	ds_read_b128 v[206:209], v243 offset:8192
	s_waitcnt lgkmcnt(3)
	v_mfma_f32_32x32x16_bf16 v[146:161], v[194:197], v[178:181], v[146:161]
	ds_read_b128 v[194:197], v244
	s_waitcnt lgkmcnt(3)
	v_mfma_f32_32x32x16_bf16 v[130:145], v[198:201], v[178:181], v[130:145]
	s_cmp_lt_u32 s97, 5
	s_cbranch_scc1 .Lad1a_4
	s_mov_b64 s[100:101], 0xc0100
	s_add_i32 m0, s67, 0x14000
	v_lshl_add_u64 v[250:251], v[220:221], 0, s[100:101]
	global_load_lds_dwordx4 v[250:251], off
.Lad1a_4:
	ds_read_b128 v[198:201], v244 offset:8192
	s_waitcnt lgkmcnt(3)
	v_mfma_f32_32x32x16_bf16 v[146:161], v[202:205], v[182:185], v[146:161]
	ds_read_b128 v[202:205], v245
	s_waitcnt lgkmcnt(3)
	v_mfma_f32_32x32x16_bf16 v[130:145], v[206:209], v[182:185], v[130:145]
	s_cmp_lt_u32 s97, 5
	s_cbranch_scc1 .Lad1a_5
	s_mov_b64 s[100:101], 0xe0100
	s_add_i32 m0, s67, 0x16000
	v_lshl_add_u64 v[250:251], v[220:221], 0, s[100:101]
	global_load_lds_dwordx4 v[250:251], off
.Lad1a_5:
	ds_read_b128 v[206:209], v245 offset:8192
	s_waitcnt lgkmcnt(3)
	v_mfma_f32_32x32x16_bf16 v[146:161], v[194:197], v[186:189], v[146:161]
	s_waitcnt lgkmcnt(2)
	v_mfma_f32_32x32x16_bf16 v[130:145], v[198:201], v[186:189], v[130:145]
	s_waitcnt lgkmcnt(1)
	v_mfma_f32_32x32x16_bf16 v[146:161], v[202:205], v[190:193], v[146:161]
	s_waitcnt lgkmcnt(0)
	v_mfma_f32_32x32x16_bf16 v[130:145], v[206:209], v[190:193], v[130:145]
	s_nop 9
	v_max_f32_e32 v194, v147, v147
	v_max_f32_e32 v195, v146, v146
	v_max_f32_e32 v194, v195, v194
	v_max3_f32 v194, v194, v148, v149
	v_max3_f32 v194, v194, v150, v151
	v_max3_f32 v194, v194, v152, v153
	v_max3_f32 v194, v194, v154, v155
	v_max3_f32 v194, v194, v156, v157
	v_max3_f32 v194, v194, v158, v159
	v_max3_f32 v194, v194, v160, v161
	v_max3_f32 v194, v194, v130, v131
	v_max3_f32 v194, v194, v132, v133
	v_max3_f32 v194, v194, v134, v135
	v_max3_f32 v194, v194, v136, v137
	v_max3_f32 v194, v194, v138, v139
	v_max3_f32 v194, v194, v140, v141
	v_max3_f32 v194, v194, v142, v143
	v_max3_f32 v194, v194, v144, v145
	v_mov_b32_e32 v195, v194
	s_nop 1
	v_permlane32_swap_b32_e32 v194, v195
	v_max_f32_e32 v195, v195, v195
	v_max_f32_e32 v194, v194, v194
	v_max_f32_e32 v194, v194, v195
	v_sub_f32_e32 v195, v194, v249
	v_cmp_ge_f32_e32 vcc, s55, v195
	v_max_f32_e32 v195, v249, v249
	v_max_f32_e32 v220, v195, v194
	v_sub_f32_e32 v194, v249, v220
	v_mul_f32_e32 v194, 0x3e0293ee, v194
	v_exp_f32_e32 v194, v194
	s_cmp_eq_u64 vcc, exec
	s_cselect_b64 s[6:7], -1, 0
	v_cndmask_b32_e64 v246, v194, 1.0, s[6:7]
	v_cmp_gt_f32_e32 vcc, 1.0, v246
	s_cbranch_vccz .LBB0_571
	s_and_saveexec_b64 s[0:1], s[4:5]
	ds_write_b32 v225, v246 offset:128
	s_or_b64 exec, exec, s[0:1]
	s_waitcnt lgkmcnt(0)
	v_add_u32_e32 v194, s65, v210
	ds_read_b128 v[206:209], v194 offset:224
	ds_read_b128 v[202:205], v194 offset:192
	ds_read_b128 v[198:201], v194 offset:160
	ds_read_b128 v[194:197], v194 offset:128
	s_waitcnt lgkmcnt(0)
	v_pk_mul_f32 v[14:15], v[14:15], v[206:207]
	s_waitcnt lgkmcnt(2)
	v_pk_mul_f32 v[10:11], v[10:11], v[202:203]
	s_waitcnt lgkmcnt(1)
	v_pk_mul_f32 v[6:7], v[6:7], v[198:199]
	v_pk_mul_f32 v[16:17], v[16:17], v[208:209]
	v_pk_mul_f32 v[12:13], v[12:13], v[204:205]
	v_pk_mul_f32 v[8:9], v[8:9], v[200:201]
	s_waitcnt lgkmcnt(0)
	v_pk_mul_f32 v[4:5], v[4:5], v[196:197]
	v_pk_mul_f32 v[2:3], v[2:3], v[194:195]
	v_pk_mul_f32 v[126:127], v[126:127], v[206:207]
	v_pk_mul_f32 v[122:123], v[122:123], v[202:203]
	v_pk_mul_f32 v[118:119], v[118:119], v[198:199]
	v_pk_mul_f32 v[128:129], v[128:129], v[208:209]
	v_pk_mul_f32 v[124:125], v[124:125], v[204:205]
	v_pk_mul_f32 v[120:121], v[120:121], v[200:201]
	v_pk_mul_f32 v[116:117], v[116:117], v[196:197]
	v_pk_mul_f32 v[114:115], v[114:115], v[194:195]
	v_pk_mul_f32 v[110:111], v[110:111], v[206:207]
	v_pk_mul_f32 v[106:107], v[106:107], v[202:203]
	v_pk_mul_f32 v[102:103], v[102:103], v[198:199]
	v_pk_mul_f32 v[112:113], v[112:113], v[208:209]
	v_pk_mul_f32 v[108:109], v[108:109], v[204:205]
	v_pk_mul_f32 v[104:105], v[104:105], v[200:201]
	v_pk_mul_f32 v[100:101], v[100:101], v[196:197]
	v_pk_mul_f32 v[98:99], v[98:99], v[194:195]
	v_pk_mul_f32 v[94:95], v[94:95], v[206:207]
	v_pk_mul_f32 v[90:91], v[90:91], v[202:203]
	v_pk_mul_f32 v[86:87], v[86:87], v[198:199]
	v_pk_mul_f32 v[96:97], v[96:97], v[208:209]
	v_pk_mul_f32 v[92:93], v[92:93], v[204:205]
	v_pk_mul_f32 v[88:89], v[88:89], v[200:201]
	v_pk_mul_f32 v[84:85], v[84:85], v[196:197]
	v_pk_mul_f32 v[82:83], v[82:83], v[194:195]
	v_pk_mul_f32 v[78:79], v[78:79], v[206:207]
	v_pk_mul_f32 v[74:75], v[74:75], v[202:203]
	v_pk_mul_f32 v[70:71], v[70:71], v[198:199]
	v_pk_mul_f32 v[80:81], v[80:81], v[208:209]
	v_pk_mul_f32 v[76:77], v[76:77], v[204:205]
	v_pk_mul_f32 v[72:73], v[72:73], v[200:201]
	v_pk_mul_f32 v[68:69], v[68:69], v[196:197]
	v_pk_mul_f32 v[66:67], v[66:67], v[194:195]
	v_pk_mul_f32 v[62:63], v[62:63], v[206:207]
	v_pk_mul_f32 v[58:59], v[58:59], v[202:203]
	v_pk_mul_f32 v[54:55], v[54:55], v[198:199]
	v_pk_mul_f32 v[64:65], v[64:65], v[208:209]
	v_pk_mul_f32 v[60:61], v[60:61], v[204:205]
	v_pk_mul_f32 v[56:57], v[56:57], v[200:201]
	v_pk_mul_f32 v[52:53], v[52:53], v[196:197]
	v_pk_mul_f32 v[50:51], v[50:51], v[194:195]
	v_pk_mul_f32 v[46:47], v[46:47], v[206:207]
	v_pk_mul_f32 v[42:43], v[42:43], v[202:203]
	v_pk_mul_f32 v[38:39], v[38:39], v[198:199]
	v_pk_mul_f32 v[48:49], v[48:49], v[208:209]
	v_pk_mul_f32 v[44:45], v[44:45], v[204:205]
	v_pk_mul_f32 v[40:41], v[40:41], v[200:201]
	v_pk_mul_f32 v[36:37], v[36:37], v[196:197]
	v_pk_mul_f32 v[34:35], v[34:35], v[194:195]
	v_pk_mul_f32 v[30:31], v[30:31], v[206:207]
	v_pk_mul_f32 v[26:27], v[26:27], v[202:203]
	v_pk_mul_f32 v[22:23], v[22:23], v[198:199]
	v_pk_mul_f32 v[32:33], v[32:33], v[208:209]
	v_pk_mul_f32 v[28:29], v[28:29], v[204:205]
	v_pk_mul_f32 v[24:25], v[24:25], v[200:201]
	v_pk_mul_f32 v[20:21], v[20:21], v[196:197]
	v_pk_mul_f32 v[18:19], v[18:19], v[194:195]
.LBB0_571:
	v_cndmask_b32_e64 v249, v220, v249, s[6:7]
	v_mul_f32_e32 v194, 0xbe0293ee, v249
	v_fmamk_f32 v146, v146, 0x3e0293ee, v194
	v_fmamk_f32 v147, v147, 0x3e0293ee, v194
	v_fmamk_f32 v148, v148, 0x3e0293ee, v194
	v_fmamk_f32 v149, v149, 0x3e0293ee, v194
	v_fmamk_f32 v150, v150, 0x3e0293ee, v194
	v_fmamk_f32 v151, v151, 0x3e0293ee, v194
	v_fmamk_f32 v152, v152, 0x3e0293ee, v194
	v_fmamk_f32 v153, v153, 0x3e0293ee, v194
	v_fmamk_f32 v154, v154, 0x3e0293ee, v194
	v_fmamk_f32 v155, v155, 0x3e0293ee, v194
	v_fmamk_f32 v156, v156, 0x3e0293ee, v194
	v_fmamk_f32 v157, v157, 0x3e0293ee, v194
	v_fmamk_f32 v158, v158, 0x3e0293ee, v194
	v_fmamk_f32 v159, v159, 0x3e0293ee, v194
	v_fmamk_f32 v160, v160, 0x3e0293ee, v194
	v_fmamk_f32 v161, v161, 0x3e0293ee, v194
	v_fmamk_f32 v130, v130, 0x3e0293ee, v194
	v_fmamk_f32 v131, v131, 0x3e0293ee, v194
	v_fmamk_f32 v132, v132, 0x3e0293ee, v194
	v_fmamk_f32 v133, v133, 0x3e0293ee, v194
	v_fmamk_f32 v134, v134, 0x3e0293ee, v194
	v_fmamk_f32 v135, v135, 0x3e0293ee, v194
	v_fmamk_f32 v136, v136, 0x3e0293ee, v194
	v_fmamk_f32 v137, v137, 0x3e0293ee, v194
	v_fmamk_f32 v138, v138, 0x3e0293ee, v194
	v_fmamk_f32 v139, v139, 0x3e0293ee, v194
	v_fmamk_f32 v140, v140, 0x3e0293ee, v194
	v_fmamk_f32 v141, v141, 0x3e0293ee, v194
	v_fmamk_f32 v142, v142, 0x3e0293ee, v194
	v_fmamk_f32 v143, v143, 0x3e0293ee, v194
	v_fmamk_f32 v144, v144, 0x3e0293ee, v194
	v_fmac_f32_e32 v194, 0x3e0293ee, v145
	v_exp_f32_e32 v145, v146
	v_exp_f32_e32 v146, v147
	v_exp_f32_e32 v147, v148
	v_exp_f32_e32 v148, v149
	v_exp_f32_e32 v149, v150
	v_exp_f32_e32 v150, v151
	v_exp_f32_e32 v151, v152
	v_exp_f32_e32 v152, v153
	v_exp_f32_e32 v153, v154
	v_exp_f32_e32 v154, v155
	v_exp_f32_e32 v155, v156
	v_exp_f32_e32 v156, v157
	v_exp_f32_e32 v157, v158
	v_exp_f32_e32 v158, v159
	v_exp_f32_e32 v159, v160
	v_exp_f32_e32 v160, v161
	v_exp_f32_e32 v161, v130
	v_add_f32_e32 v130, 0, v145
	v_add_f32_e32 v130, v146, v130
	v_add_f32_e32 v130, v147, v130
	v_add_f32_e32 v130, v148, v130
	v_add_f32_e32 v130, v149, v130
	v_add_f32_e32 v130, v150, v130
	v_add_f32_e32 v130, v151, v130
	v_add_f32_e32 v130, v152, v130
	v_add_f32_e32 v130, v153, v130
	v_add_f32_e32 v130, v154, v130
	v_add_f32_e32 v130, v155, v130
	v_add_f32_e32 v130, v156, v130
	v_add_f32_e32 v130, v157, v130
	v_exp_f32_e32 v195, v131
	v_add_f32_e32 v130, v158, v130
	v_exp_f32_e32 v196, v132
	v_add_f32_e32 v130, v159, v130
	v_exp_f32_e32 v197, v133
	v_add_f32_e32 v130, v160, v130
	v_exp_f32_e32 v198, v134
	v_add_f32_e32 v130, v161, v130
	v_exp_f32_e32 v199, v135
	v_add_f32_e32 v130, v195, v130
	v_exp_f32_e32 v200, v136
	v_add_f32_e32 v130, v196, v130
	v_exp_f32_e32 v201, v137
	v_add_f32_e32 v130, v197, v130
	v_exp_f32_e32 v202, v138
	v_add_f32_e32 v130, v198, v130
	v_exp_f32_e32 v203, v139
	v_add_f32_e32 v130, v199, v130
	v_exp_f32_e32 v204, v140
	v_add_f32_e32 v130, v200, v130
	v_exp_f32_e32 v205, v141
	v_add_f32_e32 v130, v201, v130
	v_exp_f32_e32 v206, v142
	v_add_f32_e32 v130, v202, v130
	v_exp_f32_e32 v207, v143
	v_add_f32_e32 v130, v203, v130
	v_exp_f32_e32 v208, v144
	v_add_f32_e32 v130, v204, v130
	v_exp_f32_e32 v194, v194
	v_add_f32_e32 v130, v205, v130
	v_add_f32_e32 v130, v206, v130
	v_add_f32_e32 v130, v207, v130
	v_add_f32_e32 v130, v208, v130
	v_add_f32_e32 v247, v194, v130
	v_mov_b32_e32 v248, v247
	s_nop 1
	v_permlane32_swap_b32_e32 v247, v248
	v_cvt_pk_bf16_f32 v130, v145, v146
	v_cvt_pk_bf16_f32 v131, v147, v148
	v_cvt_pk_bf16_f32 v132, v149, v150
	v_cvt_pk_bf16_f32 v133, v151, v152
	v_cvt_pk_bf16_f32 v134, v153, v154
	v_cvt_pk_bf16_f32 v135, v155, v156
	v_cvt_pk_bf16_f32 v136, v157, v158
	v_cvt_pk_bf16_f32 v137, v159, v160
	v_cvt_pk_bf16_f32 v138, v161, v195
	v_cvt_pk_bf16_f32 v139, v196, v197
	v_cvt_pk_bf16_f32 v140, v198, v199
	v_cvt_pk_bf16_f32 v141, v200, v201
	v_cvt_pk_bf16_f32 v142, v202, v203
	v_cvt_pk_bf16_f32 v143, v204, v205
	v_cvt_pk_bf16_f32 v144, v206, v207
	v_cvt_pk_bf16_f32 v145, v208, v194
	s_nop 0
	v_permlane32_swap_b32_e32 v130, v132
	v_permlane32_swap_b32_e32 v131, v133
	v_permlane32_swap_b32_e32 v134, v136
	v_permlane32_swap_b32_e32 v135, v137
	v_permlane32_swap_b32_e32 v138, v140
	v_permlane32_swap_b32_e32 v139, v141
	v_permlane32_swap_b32_e32 v142, v144
	v_permlane32_swap_b32_e32 v143, v145
	ds_read_b64_tr_b16 v[146:147], v224 offset:0
	ds_read_b64_tr_b16 v[148:149], v224 offset:0x800
	ds_read_b64_tr_b16 v[150:151], v224 offset:0x1000
	ds_read_b64_tr_b16 v[152:153], v224 offset:0x1800
	ds_read_b64_tr_b16 v[154:155], v224 offset:0x2000
	ds_read_b64_tr_b16 v[156:157], v224 offset:0x2800
	ds_read_b64_tr_b16 v[158:159], v224 offset:0x3000
	ds_read_b64_tr_b16 v[160:161], v224 offset:0x3800
	s_waitcnt lgkmcnt(0)
	s_nop 0
	v_mfma_f32_32x32x16_bf16 v[2:17], v[130:133], v[146:149], v[2:17]
	ds_read_b64_tr_b16 v[146:147], v224 offset:0x200
	ds_read_b64_tr_b16 v[148:149], v224 offset:0xa00
	v_mfma_f32_32x32x16_bf16 v[2:17], v[134:137], v[150:153], v[2:17]
	ds_read_b64_tr_b16 v[150:151], v224 offset:0x1200
	ds_read_b64_tr_b16 v[152:153], v224 offset:0x1a00
	v_mfma_f32_32x32x16_bf16 v[2:17], v[138:141], v[154:157], v[2:17]
	ds_read_b64_tr_b16 v[154:155], v224 offset:0x2200
	ds_read_b64_tr_b16 v[156:157], v224 offset:0x2a00
	v_mfma_f32_32x32x16_bf16 v[2:17], v[142:145], v[158:161], v[2:17]
	ds_read_b64_tr_b16 v[158:159], v224 offset:0x3200
	ds_read_b64_tr_b16 v[160:161], v224 offset:0x3a00
	s_waitcnt lgkmcnt(0)
	v_mfma_f32_32x32x16_bf16 v[114:129], v[130:133], v[146:149], v[114:129]
	ds_read_b64_tr_b16 v[146:147], v224 offset:0x400
	ds_read_b64_tr_b16 v[148:149], v224 offset:0xc00
	v_mfma_f32_32x32x16_bf16 v[114:129], v[134:137], v[150:153], v[114:129]
	ds_read_b64_tr_b16 v[150:151], v224 offset:0x1400
	ds_read_b64_tr_b16 v[152:153], v224 offset:0x1c00
	v_mfma_f32_32x32x16_bf16 v[114:129], v[138:141], v[154:157], v[114:129]
	ds_read_b64_tr_b16 v[154:155], v224 offset:0x2400
	ds_read_b64_tr_b16 v[156:157], v224 offset:0x2c00
	v_mfma_f32_32x32x16_bf16 v[114:129], v[142:145], v[158:161], v[114:129]
	ds_read_b64_tr_b16 v[158:159], v224 offset:0x3400
	ds_read_b64_tr_b16 v[160:161], v224 offset:0x3c00
	s_waitcnt lgkmcnt(0)
	v_mfma_f32_32x32x16_bf16 v[98:113], v[130:133], v[146:149], v[98:113]
	ds_read_b64_tr_b16 v[146:147], v224 offset:0x600
	ds_read_b64_tr_b16 v[148:149], v224 offset:0xe00
	v_mfma_f32_32x32x16_bf16 v[98:113], v[134:137], v[150:153], v[98:113]
	ds_read_b64_tr_b16 v[150:151], v224 offset:0x1600
	ds_read_b64_tr_b16 v[152:153], v224 offset:0x1e00
	v_mfma_f32_32x32x16_bf16 v[98:113], v[138:141], v[154:157], v[98:113]
	ds_read_b64_tr_b16 v[154:155], v224 offset:0x2600
	ds_read_b64_tr_b16 v[156:157], v224 offset:0x2e00
	v_mfma_f32_32x32x16_bf16 v[98:113], v[142:145], v[158:161], v[98:113]
	ds_read_b64_tr_b16 v[158:159], v224 offset:0x3600
	ds_read_b64_tr_b16 v[160:161], v224 offset:0x3e00
	s_waitcnt lgkmcnt(0)
	v_mfma_f32_32x32x16_bf16 v[82:97], v[130:133], v[146:149], v[82:97]
	ds_read_b64_tr_b16 v[146:147], v234 offset:0
	ds_read_b64_tr_b16 v[148:149], v234 offset:0x800
	v_mfma_f32_32x32x16_bf16 v[82:97], v[134:137], v[150:153], v[82:97]
	ds_read_b64_tr_b16 v[150:151], v234 offset:0x1000
	ds_read_b64_tr_b16 v[152:153], v234 offset:0x1800
	v_mfma_f32_32x32x16_bf16 v[82:97], v[138:141], v[154:157], v[82:97]
	ds_read_b64_tr_b16 v[154:155], v234 offset:0x2000
	ds_read_b64_tr_b16 v[156:157], v234 offset:0x2800
	v_mfma_f32_32x32x16_bf16 v[82:97], v[142:145], v[158:161], v[82:97]
	ds_read_b64_tr_b16 v[158:159], v234 offset:0x3000
	ds_read_b64_tr_b16 v[160:161], v234 offset:0x3800
	s_waitcnt lgkmcnt(0)
	v_mfma_f32_32x32x16_bf16 v[66:81], v[130:133], v[146:149], v[66:81]
	ds_read_b64_tr_b16 v[146:147], v234 offset:0x200
	ds_read_b64_tr_b16 v[148:149], v234 offset:0xa00
	v_mfma_f32_32x32x16_bf16 v[66:81], v[134:137], v[150:153], v[66:81]
	ds_read_b64_tr_b16 v[150:151], v234 offset:0x1200
	ds_read_b64_tr_b16 v[152:153], v234 offset:0x1a00
	v_mfma_f32_32x32x16_bf16 v[66:81], v[138:141], v[154:157], v[66:81]
	ds_read_b64_tr_b16 v[154:155], v234 offset:0x2200
	ds_read_b64_tr_b16 v[156:157], v234 offset:0x2a00
	v_mfma_f32_32x32x16_bf16 v[66:81], v[142:145], v[158:161], v[66:81]
	ds_read_b64_tr_b16 v[158:159], v234 offset:0x3200
	ds_read_b64_tr_b16 v[160:161], v234 offset:0x3a00
	s_waitcnt lgkmcnt(0)
	v_mfma_f32_32x32x16_bf16 v[50:65], v[130:133], v[146:149], v[50:65]
	ds_read_b64_tr_b16 v[146:147], v234 offset:0x400
	ds_read_b64_tr_b16 v[148:149], v234 offset:0xc00
	v_mfma_f32_32x32x16_bf16 v[50:65], v[134:137], v[150:153], v[50:65]
	ds_read_b64_tr_b16 v[150:151], v234 offset:0x1400
	ds_read_b64_tr_b16 v[152:153], v234 offset:0x1c00
	v_mfma_f32_32x32x16_bf16 v[50:65], v[138:141], v[154:157], v[50:65]
	ds_read_b64_tr_b16 v[154:155], v234 offset:0x2400
	ds_read_b64_tr_b16 v[156:157], v234 offset:0x2c00
	v_mfma_f32_32x32x16_bf16 v[50:65], v[142:145], v[158:161], v[50:65]
	ds_read_b64_tr_b16 v[158:159], v234 offset:0x3400
	ds_read_b64_tr_b16 v[160:161], v234 offset:0x3c00
	s_waitcnt lgkmcnt(0)
	v_mfma_f32_32x32x16_bf16 v[34:49], v[130:133], v[146:149], v[34:49]
	ds_read_b64_tr_b16 v[146:147], v234 offset:0x600
	ds_read_b64_tr_b16 v[148:149], v234 offset:0xe00
	v_mfma_f32_32x32x16_bf16 v[34:49], v[134:137], v[150:153], v[34:49]
	ds_read_b64_tr_b16 v[150:151], v234 offset:0x1600
	ds_read_b64_tr_b16 v[152:153], v234 offset:0x1e00
	v_mfma_f32_32x32x16_bf16 v[34:49], v[138:141], v[154:157], v[34:49]
	ds_read_b64_tr_b16 v[154:155], v234 offset:0x2600
	ds_read_b64_tr_b16 v[156:157], v234 offset:0x2e00
	v_mfma_f32_32x32x16_bf16 v[34:49], v[142:145], v[158:161], v[34:49]
	ds_read_b64_tr_b16 v[158:159], v234 offset:0x3600
	ds_read_b64_tr_b16 v[160:161], v234 offset:0x3e00
	s_waitcnt lgkmcnt(0)
	v_mfma_f32_32x32x16_bf16 v[18:33], v[130:133], v[146:149], v[18:33]
	s_barrier
	v_mfma_f32_32x32x16_bf16 v[18:33], v[134:137], v[150:153], v[18:33]
	v_mfma_f32_32x32x16_bf16 v[18:33], v[138:141], v[154:157], v[18:33]
	v_mfma_f32_32x32x16_bf16 v[18:33], v[142:145], v[158:161], v[18:33]
	s_add_i32 s14, s97, -1
	v_lshl_add_u64 v[222:223], v[216:217], 0, s[44:45]
	v_lshl_add_u64 v[220:221], v[218:219], 0, s[44:45]
	s_mov_b64 s[70:71], 0xa0000
	s_waitcnt vmcnt(0)
.LBB0_573:
.LBB0_575:
	s_barrier
	ds_read_b128 v[194:197], v238 offset:16384
	ds_read_b128 v[198:201], v239 offset:16384
	ds_read_b128 v[202:205], v238 offset:24576
	ds_read_b128 v[206:209], v239 offset:24576
	s_waitcnt lgkmcnt(3)
	v_mfma_f32_32x32x16_bf16 v[146:161], v[194:197], v[162:165], 0
	ds_read_b128 v[194:197], v240 offset:16384
	s_waitcnt lgkmcnt(3)
	v_mfma_f32_32x32x16_bf16 v[146:161], v[198:201], v[166:169], v[146:161]
	s_cmp_ge_u32 s14, s17
	s_cbranch_scc1 .Lad1b_0
	s_mov_b64 s[100:101], 0x80000
	s_mov_b32 m0, s67
	v_lshl_add_u64 v[250:251], v[222:223], 0, s[100:101]
	global_load_lds_dwordx4 v[250:251], off
.Lad1b_0:
	ds_read_b128 v[198:201], v240 offset:24576
	s_waitcnt lgkmcnt(3)
	v_mfma_f32_32x32x16_bf16 v[130:145], v[202:205], v[162:165], 0
	ds_read_b128 v[202:205], v241 offset:16384
	s_waitcnt lgkmcnt(3)
	v_mfma_f32_32x32x16_bf16 v[130:145], v[206:209], v[166:169], v[130:145]
	s_cmp_ge_u32 s14, s17
	s_cbranch_scc1 .Lad1b_1
	s_mov_b64 s[100:101], 0xa0000
	s_mov_b32 m0, s72
	v_lshl_add_u64 v[250:251], v[222:223], 0, s[100:101]
	global_load_lds_dwordx4 v[250:251], off
.Lad1b_1:
	ds_read_b128 v[206:209], v241 offset:24576
	s_waitcnt lgkmcnt(3)
	v_mfma_f32_32x32x16_bf16 v[146:161], v[194:197], v[170:173], v[146:161]
	ds_read_b128 v[194:197], v242 offset:16384
	s_waitcnt lgkmcnt(3)
	v_mfma_f32_32x32x16_bf16 v[130:145], v[198:201], v[170:173], v[130:145]
	s_cmp_ge_u32 s14, s17
	s_cbranch_scc1 .Lad1b_2
	s_mov_b64 s[100:101], 0x80000
	s_mov_b32 m0, s73
	v_lshl_add_u64 v[250:251], v[220:221], 0, s[100:101]
	global_load_lds_dwordx4 v[250:251], off
.Lad1b_2:
	ds_read_b128 v[198:201], v242 offset:24576
	s_waitcnt lgkmcnt(3)
	v_mfma_f32_32x32x16_bf16 v[146:161], v[202:205], v[174:177], v[146:161]
	ds_read_b128 v[202:205], v243 offset:16384
	s_waitcnt lgkmcnt(3)
	v_mfma_f32_32x32x16_bf16 v[130:145], v[206:209], v[174:177], v[130:145]
	s_cmp_ge_u32 s14, s17
	s_cbranch_scc1 .Lad1b_3
	s_mov_b64 s[100:101], 0xa0000
	s_mov_b32 m0, s74
	v_lshl_add_u64 v[250:251], v[220:221], 0, s[100:101]
	global_load_lds_dwordx4 v[250:251], off
.Lad1b_3:
	ds_read_b128 v[206:209], v243 offset:24576
	s_waitcnt lgkmcnt(3)
	v_mfma_f32_32x32x16_bf16 v[146:161], v[194:197], v[178:181], v[146:161]
	ds_read_b128 v[194:197], v244 offset:16384
	s_waitcnt lgkmcnt(3)
	v_mfma_f32_32x32x16_bf16 v[130:145], v[198:201], v[178:181], v[130:145]
	s_cmp_ge_u32 s14, s17
	s_cbranch_scc1 .Lad1b_4
	s_mov_b64 s[100:101], 0x80100
	s_mov_b32 m0, s75
	v_lshl_add_u64 v[250:251], v[220:221], 0, s[100:101]
	global_load_lds_dwordx4 v[250:251], off
.Lad1b_4:
	ds_read_b128 v[198:201], v244 offset:24576
	s_waitcnt lgkmcnt(3)
	v_mfma_f32_32x32x16_bf16 v[146:161], v[202:205], v[182:185], v[146:161]
	ds_read_b128 v[202:205], v245 offset:16384
	s_waitcnt lgkmcnt(3)
	v_mfma_f32_32x32x16_bf16 v[130:145], v[206:209], v[182:185], v[130:145]
	s_cmp_ge_u32 s14, s17
	s_cbranch_scc1 .Lad1b_5
	s_mov_b64 s[100:101], 0xa0100
	s_mov_b32 m0, s76
	v_lshl_add_u64 v[250:251], v[220:221], 0, s[100:101]
	global_load_lds_dwordx4 v[250:251], off
.Lad1b_5:
	ds_read_b128 v[206:209], v245 offset:24576
	s_waitcnt lgkmcnt(3)
	v_mfma_f32_32x32x16_bf16 v[146:161], v[194:197], v[186:189], v[146:161]
	s_waitcnt lgkmcnt(2)
	v_mfma_f32_32x32x16_bf16 v[130:145], v[198:201], v[186:189], v[130:145]
	s_waitcnt lgkmcnt(1)
	v_mfma_f32_32x32x16_bf16 v[146:161], v[202:205], v[190:193], v[146:161]
	s_waitcnt lgkmcnt(0)
	v_mfma_f32_32x32x16_bf16 v[130:145], v[206:209], v[190:193], v[130:145]
	s_nop 9
	v_max_f32_e32 v194, v147, v147
	v_max_f32_e32 v195, v146, v146
	v_max_f32_e32 v194, v195, v194
	v_max3_f32 v194, v194, v148, v149
	v_max3_f32 v194, v194, v150, v151
	v_max3_f32 v194, v194, v152, v153
	v_max3_f32 v194, v194, v154, v155
	v_max3_f32 v194, v194, v156, v157
	v_max3_f32 v194, v194, v158, v159
	v_max3_f32 v194, v194, v160, v161
	v_max3_f32 v194, v194, v130, v131
	v_max3_f32 v194, v194, v132, v133
	v_max3_f32 v194, v194, v134, v135
	v_max3_f32 v194, v194, v136, v137
	v_max3_f32 v194, v194, v138, v139
	v_max3_f32 v194, v194, v140, v141
	v_max3_f32 v194, v194, v142, v143
	v_max3_f32 v194, v194, v144, v145
	v_mov_b32_e32 v195, v194
	s_nop 1
	v_permlane32_swap_b32_e32 v194, v195
	v_max_f32_e32 v195, v195, v195
	v_max_f32_e32 v194, v194, v194
	v_max_f32_e32 v194, v194, v195
	v_sub_f32_e32 v195, v194, v249
	v_cmp_ge_f32_e32 vcc, s55, v195
	v_max_f32_e32 v195, v249, v249
	v_max_f32_e32 v251, v195, v194
	v_sub_f32_e32 v194, v249, v251
	v_mul_f32_e32 v194, 0x3e0293ee, v194
	v_exp_f32_e32 v194, v194
	s_cmp_eq_u64 vcc, exec
	s_cselect_b64 s[6:7], -1, 0
	v_cndmask_b32_e64 v250, v194, 1.0, s[6:7]
	v_cmp_gt_f32_e32 vcc, 1.0, v250
	s_cbranch_vccz .LBB0_579
	s_and_saveexec_b64 s[0:1], s[4:5]
	ds_write_b32 v225, v250 offset:128
	s_or_b64 exec, exec, s[0:1]
	s_waitcnt lgkmcnt(0)
	v_add_u32_e32 v194, s65, v210
	ds_read_b128 v[206:209], v194 offset:224
	ds_read_b128 v[202:205], v194 offset:192
	ds_read_b128 v[198:201], v194 offset:160
	ds_read_b128 v[194:197], v194 offset:128
	s_waitcnt lgkmcnt(0)
	v_pk_mul_f32 v[14:15], v[14:15], v[206:207]
	v_pk_mul_f32 v[10:11], v[10:11], v[202:203]
	v_pk_mul_f32 v[6:7], v[6:7], v[198:199]
	v_pk_mul_f32 v[16:17], v[16:17], v[208:209]
	v_pk_mul_f32 v[12:13], v[12:13], v[204:205]
	v_pk_mul_f32 v[8:9], v[8:9], v[200:201]
	v_pk_mul_f32 v[4:5], v[4:5], v[196:197]
	v_pk_mul_f32 v[2:3], v[2:3], v[194:195]
	v_pk_mul_f32 v[126:127], v[126:127], v[206:207]
	v_pk_mul_f32 v[122:123], v[122:123], v[202:203]
	v_pk_mul_f32 v[118:119], v[118:119], v[198:199]
	v_pk_mul_f32 v[128:129], v[128:129], v[208:209]
	v_pk_mul_f32 v[124:125], v[124:125], v[204:205]
	v_pk_mul_f32 v[120:121], v[120:121], v[200:201]
	v_pk_mul_f32 v[116:117], v[116:117], v[196:197]
	v_pk_mul_f32 v[114:115], v[114:115], v[194:195]
	v_pk_mul_f32 v[110:111], v[110:111], v[206:207]
	v_pk_mul_f32 v[106:107], v[106:107], v[202:203]
	v_pk_mul_f32 v[102:103], v[102:103], v[198:199]
	v_pk_mul_f32 v[112:113], v[112:113], v[208:209]
	v_pk_mul_f32 v[108:109], v[108:109], v[204:205]
	v_pk_mul_f32 v[104:105], v[104:105], v[200:201]
	v_pk_mul_f32 v[100:101], v[100:101], v[196:197]
	v_pk_mul_f32 v[98:99], v[98:99], v[194:195]
	v_pk_mul_f32 v[94:95], v[94:95], v[206:207]
	v_pk_mul_f32 v[90:91], v[90:91], v[202:203]
	v_pk_mul_f32 v[86:87], v[86:87], v[198:199]
	v_pk_mul_f32 v[96:97], v[96:97], v[208:209]
	v_pk_mul_f32 v[92:93], v[92:93], v[204:205]
	v_pk_mul_f32 v[88:89], v[88:89], v[200:201]
	v_pk_mul_f32 v[84:85], v[84:85], v[196:197]
	v_pk_mul_f32 v[82:83], v[82:83], v[194:195]
	v_pk_mul_f32 v[78:79], v[78:79], v[206:207]
	v_pk_mul_f32 v[74:75], v[74:75], v[202:203]
	v_pk_mul_f32 v[70:71], v[70:71], v[198:199]
	v_pk_mul_f32 v[80:81], v[80:81], v[208:209]
	v_pk_mul_f32 v[76:77], v[76:77], v[204:205]
	v_pk_mul_f32 v[72:73], v[72:73], v[200:201]
	v_pk_mul_f32 v[68:69], v[68:69], v[196:197]
	v_pk_mul_f32 v[66:67], v[66:67], v[194:195]
	v_pk_mul_f32 v[62:63], v[62:63], v[206:207]
	v_pk_mul_f32 v[58:59], v[58:59], v[202:203]
	v_pk_mul_f32 v[54:55], v[54:55], v[198:199]
	v_pk_mul_f32 v[64:65], v[64:65], v[208:209]
	v_pk_mul_f32 v[60:61], v[60:61], v[204:205]
	v_pk_mul_f32 v[56:57], v[56:57], v[200:201]
	v_pk_mul_f32 v[52:53], v[52:53], v[196:197]
	v_pk_mul_f32 v[50:51], v[50:51], v[194:195]
	v_pk_mul_f32 v[46:47], v[46:47], v[206:207]
	v_pk_mul_f32 v[42:43], v[42:43], v[202:203]
	v_pk_mul_f32 v[38:39], v[38:39], v[198:199]
	v_pk_mul_f32 v[48:49], v[48:49], v[208:209]
	v_pk_mul_f32 v[44:45], v[44:45], v[204:205]
	v_pk_mul_f32 v[40:41], v[40:41], v[200:201]
	v_pk_mul_f32 v[36:37], v[36:37], v[196:197]
	v_pk_mul_f32 v[34:35], v[34:35], v[194:195]
	v_pk_mul_f32 v[30:31], v[30:31], v[206:207]
	v_pk_mul_f32 v[26:27], v[26:27], v[202:203]
	v_pk_mul_f32 v[22:23], v[22:23], v[198:199]
	v_pk_mul_f32 v[32:33], v[32:33], v[208:209]
	v_pk_mul_f32 v[28:29], v[28:29], v[204:205]
	v_pk_mul_f32 v[24:25], v[24:25], v[200:201]
	v_pk_mul_f32 v[20:21], v[20:21], v[196:197]
	v_pk_mul_f32 v[18:19], v[18:19], v[194:195]
.LBB0_579:
	v_cndmask_b32_e64 v249, v251, v249, s[6:7]
	v_mul_f32_e32 v194, 0xbe0293ee, v249
	v_fmamk_f32 v146, v146, 0x3e0293ee, v194
	v_fmamk_f32 v147, v147, 0x3e0293ee, v194
	v_fmamk_f32 v148, v148, 0x3e0293ee, v194
	v_fmamk_f32 v149, v149, 0x3e0293ee, v194
	v_fmamk_f32 v150, v150, 0x3e0293ee, v194
	v_fmamk_f32 v151, v151, 0x3e0293ee, v194
	v_fmamk_f32 v152, v152, 0x3e0293ee, v194
	v_fmamk_f32 v153, v153, 0x3e0293ee, v194
	v_fmamk_f32 v154, v154, 0x3e0293ee, v194
	v_fmamk_f32 v155, v155, 0x3e0293ee, v194
	v_fmamk_f32 v156, v156, 0x3e0293ee, v194
	v_fmamk_f32 v157, v157, 0x3e0293ee, v194
	v_fmamk_f32 v158, v158, 0x3e0293ee, v194
	v_fmamk_f32 v159, v159, 0x3e0293ee, v194
	v_fmamk_f32 v160, v160, 0x3e0293ee, v194
	v_fmamk_f32 v161, v161, 0x3e0293ee, v194
	v_fmamk_f32 v130, v130, 0x3e0293ee, v194
	v_fmamk_f32 v131, v131, 0x3e0293ee, v194
	v_fmamk_f32 v132, v132, 0x3e0293ee, v194
	v_fmamk_f32 v133, v133, 0x3e0293ee, v194
	v_fmamk_f32 v134, v134, 0x3e0293ee, v194
	v_fmamk_f32 v135, v135, 0x3e0293ee, v194
	v_fmamk_f32 v136, v136, 0x3e0293ee, v194
	v_fmamk_f32 v137, v137, 0x3e0293ee, v194
	v_fmamk_f32 v138, v138, 0x3e0293ee, v194
	v_fmamk_f32 v139, v139, 0x3e0293ee, v194
	v_fmamk_f32 v140, v140, 0x3e0293ee, v194
	v_fmamk_f32 v141, v141, 0x3e0293ee, v194
	v_fmamk_f32 v142, v142, 0x3e0293ee, v194
	v_fmamk_f32 v143, v143, 0x3e0293ee, v194
	v_fmamk_f32 v144, v144, 0x3e0293ee, v194
	v_fmac_f32_e32 v194, 0x3e0293ee, v145
	v_exp_f32_e32 v145, v146
	v_exp_f32_e32 v195, v147
	v_exp_f32_e32 v148, v148
	v_exp_f32_e32 v149, v149
	v_exp_f32_e32 v150, v150
	v_exp_f32_e32 v196, v130
	v_add_f32_e32 v130, 0, v145
	v_exp_f32_e32 v151, v151
	v_add_f32_e32 v130, v195, v130
	v_exp_f32_e32 v152, v152
	v_add_f32_e32 v130, v148, v130
	v_exp_f32_e32 v153, v153
	v_add_f32_e32 v130, v149, v130
	v_exp_f32_e32 v154, v154
	v_add_f32_e32 v130, v150, v130
	v_exp_f32_e32 v155, v155
	v_add_f32_e32 v130, v151, v130
	v_exp_f32_e32 v156, v156
	v_add_f32_e32 v130, v152, v130
	v_exp_f32_e32 v157, v157
	v_add_f32_e32 v130, v153, v130
	v_exp_f32_e32 v158, v158
	v_add_f32_e32 v130, v154, v130
	v_exp_f32_e32 v159, v159
	v_add_f32_e32 v130, v155, v130
	v_exp_f32_e32 v160, v160
	v_add_f32_e32 v130, v156, v130
	v_exp_f32_e32 v161, v161
	v_add_f32_e32 v130, v157, v130
	v_add_f32_e32 v130, v158, v130
	v_exp_f32_e32 v197, v131
	v_add_f32_e32 v130, v159, v130
	v_exp_f32_e32 v198, v132
	v_add_f32_e32 v130, v160, v130
	v_exp_f32_e32 v199, v133
	v_add_f32_e32 v130, v161, v130
	v_exp_f32_e32 v200, v134
	v_add_f32_e32 v130, v196, v130
	v_exp_f32_e32 v201, v135
	v_add_f32_e32 v130, v197, v130
	v_exp_f32_e32 v202, v136
	v_add_f32_e32 v130, v198, v130
	v_exp_f32_e32 v203, v137
	v_add_f32_e32 v130, v199, v130
	v_exp_f32_e32 v204, v138
	v_add_f32_e32 v130, v200, v130
	v_exp_f32_e32 v205, v139
	v_add_f32_e32 v130, v201, v130
	v_exp_f32_e32 v206, v140
	v_add_f32_e32 v130, v202, v130
	v_exp_f32_e32 v207, v141
	v_add_f32_e32 v130, v203, v130
	v_exp_f32_e32 v208, v142
	v_add_f32_e32 v130, v204, v130
	v_exp_f32_e32 v209, v143
	v_add_f32_e32 v130, v205, v130
	v_exp_f32_e32 v251, v144
	v_add_f32_e32 v130, v206, v130
	v_exp_f32_e32 v194, v194
	v_add_f32_e32 v130, v207, v130
	v_add_f32_e32 v130, v208, v130
	v_add_f32_e32 v130, v209, v130
	v_add_f32_e32 v130, v251, v130
	v_add_f32_e32 v146, v194, v130
	v_mov_b32_e32 v147, v146
	s_nop 1
	v_permlane32_swap_b32_e32 v146, v147
	v_cvt_pk_bf16_f32 v130, v145, v195
	v_cvt_pk_bf16_f32 v131, v148, v149
	v_cvt_pk_bf16_f32 v132, v150, v151
	v_cvt_pk_bf16_f32 v133, v152, v153
	v_cvt_pk_bf16_f32 v134, v154, v155
	v_cvt_pk_bf16_f32 v135, v156, v157
	v_cvt_pk_bf16_f32 v136, v158, v159
	v_cvt_pk_bf16_f32 v137, v160, v161
	v_cvt_pk_bf16_f32 v138, v196, v197
	v_cvt_pk_bf16_f32 v139, v198, v199
	v_cvt_pk_bf16_f32 v140, v200, v201
	v_cvt_pk_bf16_f32 v141, v202, v203
	v_cvt_pk_bf16_f32 v142, v204, v205
	v_cvt_pk_bf16_f32 v143, v206, v207
	v_cvt_pk_bf16_f32 v144, v208, v209
	v_cvt_pk_bf16_f32 v145, v251, v194
	s_nop 0
	v_permlane32_swap_b32_e32 v130, v132
	v_permlane32_swap_b32_e32 v131, v133
	v_permlane32_swap_b32_e32 v134, v136
	v_permlane32_swap_b32_e32 v135, v137
	v_permlane32_swap_b32_e32 v138, v140
	v_permlane32_swap_b32_e32 v139, v141
	v_permlane32_swap_b32_e32 v142, v144
	v_permlane32_swap_b32_e32 v143, v145
	ds_read_b64_tr_b16 v[148:149], v235 offset:0
	ds_read_b64_tr_b16 v[150:151], v235 offset:0x800
	ds_read_b64_tr_b16 v[152:153], v235 offset:0x1000
	ds_read_b64_tr_b16 v[154:155], v235 offset:0x1800
	ds_read_b64_tr_b16 v[156:157], v235 offset:0x2000
	ds_read_b64_tr_b16 v[158:159], v235 offset:0x2800
	ds_read_b64_tr_b16 v[194:195], v235 offset:0x3000
	ds_read_b64_tr_b16 v[196:197], v235 offset:0x3800
	s_waitcnt lgkmcnt(0)
	s_nop 0
	v_mfma_f32_32x32x16_bf16 v[2:17], v[130:133], v[148:151], v[2:17]
	ds_read_b64_tr_b16 v[148:149], v235 offset:0x200
	ds_read_b64_tr_b16 v[150:151], v235 offset:0xa00
	v_mfma_f32_32x32x16_bf16 v[2:17], v[134:137], v[152:155], v[2:17]
	ds_read_b64_tr_b16 v[152:153], v235 offset:0x1200
	ds_read_b64_tr_b16 v[154:155], v235 offset:0x1a00
	v_mfma_f32_32x32x16_bf16 v[2:17], v[138:141], v[156:159], v[2:17]
	ds_read_b64_tr_b16 v[156:157], v235 offset:0x2200
	ds_read_b64_tr_b16 v[158:159], v235 offset:0x2a00
	v_mfma_f32_32x32x16_bf16 v[2:17], v[142:145], v[194:197], v[2:17]
	ds_read_b64_tr_b16 v[194:195], v235 offset:0x3200
	ds_read_b64_tr_b16 v[196:197], v235 offset:0x3a00
	s_waitcnt lgkmcnt(0)
	v_mfma_f32_32x32x16_bf16 v[114:129], v[130:133], v[148:151], v[114:129]
	ds_read_b64_tr_b16 v[148:149], v235 offset:0x400
	ds_read_b64_tr_b16 v[150:151], v235 offset:0xc00
	v_mfma_f32_32x32x16_bf16 v[114:129], v[134:137], v[152:155], v[114:129]
	ds_read_b64_tr_b16 v[152:153], v235 offset:0x1400
	ds_read_b64_tr_b16 v[154:155], v235 offset:0x1c00
	v_mfma_f32_32x32x16_bf16 v[114:129], v[138:141], v[156:159], v[114:129]
	ds_read_b64_tr_b16 v[156:157], v235 offset:0x2400
	ds_read_b64_tr_b16 v[158:159], v235 offset:0x2c00
	v_mfma_f32_32x32x16_bf16 v[114:129], v[142:145], v[194:197], v[114:129]
	ds_read_b64_tr_b16 v[194:195], v235 offset:0x3400
	ds_read_b64_tr_b16 v[196:197], v235 offset:0x3c00
	s_waitcnt lgkmcnt(0)
	v_mfma_f32_32x32x16_bf16 v[98:113], v[130:133], v[148:151], v[98:113]
	ds_read_b64_tr_b16 v[148:149], v235 offset:0x600
	ds_read_b64_tr_b16 v[150:151], v235 offset:0xe00
	v_mfma_f32_32x32x16_bf16 v[98:113], v[134:137], v[152:155], v[98:113]
	ds_read_b64_tr_b16 v[152:153], v235 offset:0x1600
	ds_read_b64_tr_b16 v[154:155], v235 offset:0x1e00
	v_mfma_f32_32x32x16_bf16 v[98:113], v[138:141], v[156:159], v[98:113]
	ds_read_b64_tr_b16 v[156:157], v235 offset:0x2600
	ds_read_b64_tr_b16 v[158:159], v235 offset:0x2e00
	v_mfma_f32_32x32x16_bf16 v[98:113], v[142:145], v[194:197], v[98:113]
	ds_read_b64_tr_b16 v[194:195], v235 offset:0x3600
	ds_read_b64_tr_b16 v[196:197], v235 offset:0x3e00
	s_waitcnt lgkmcnt(0)
	v_mfma_f32_32x32x16_bf16 v[82:97], v[130:133], v[148:151], v[82:97]
	ds_read_b64_tr_b16 v[148:149], v236 offset:0
	ds_read_b64_tr_b16 v[150:151], v236 offset:0x800
	v_mfma_f32_32x32x16_bf16 v[82:97], v[134:137], v[152:155], v[82:97]
	ds_read_b64_tr_b16 v[152:153], v236 offset:0x1000
	ds_read_b64_tr_b16 v[154:155], v236 offset:0x1800
	v_mfma_f32_32x32x16_bf16 v[82:97], v[138:141], v[156:159], v[82:97]
	ds_read_b64_tr_b16 v[156:157], v236 offset:0x2000
	ds_read_b64_tr_b16 v[158:159], v236 offset:0x2800
	v_mfma_f32_32x32x16_bf16 v[82:97], v[142:145], v[194:197], v[82:97]
	ds_read_b64_tr_b16 v[194:195], v236 offset:0x3000
	ds_read_b64_tr_b16 v[196:197], v236 offset:0x3800
	s_waitcnt lgkmcnt(0)
	v_mfma_f32_32x32x16_bf16 v[66:81], v[130:133], v[148:151], v[66:81]
	ds_read_b64_tr_b16 v[148:149], v236 offset:0x200
	ds_read_b64_tr_b16 v[150:151], v236 offset:0xa00
	v_mfma_f32_32x32x16_bf16 v[66:81], v[134:137], v[152:155], v[66:81]
	ds_read_b64_tr_b16 v[152:153], v236 offset:0x1200
	ds_read_b64_tr_b16 v[154:155], v236 offset:0x1a00
	v_mfma_f32_32x32x16_bf16 v[66:81], v[138:141], v[156:159], v[66:81]
	ds_read_b64_tr_b16 v[156:157], v236 offset:0x2200
	ds_read_b64_tr_b16 v[158:159], v236 offset:0x2a00
	v_mfma_f32_32x32x16_bf16 v[66:81], v[142:145], v[194:197], v[66:81]
	ds_read_b64_tr_b16 v[194:195], v236 offset:0x3200
	ds_read_b64_tr_b16 v[196:197], v236 offset:0x3a00
	s_waitcnt lgkmcnt(0)
	v_mfma_f32_32x32x16_bf16 v[50:65], v[130:133], v[148:151], v[50:65]
	ds_read_b64_tr_b16 v[148:149], v236 offset:0x400
	ds_read_b64_tr_b16 v[150:151], v236 offset:0xc00
	v_mfma_f32_32x32x16_bf16 v[50:65], v[134:137], v[152:155], v[50:65]
	ds_read_b64_tr_b16 v[152:153], v236 offset:0x1400
	ds_read_b64_tr_b16 v[154:155], v236 offset:0x1c00
	v_mfma_f32_32x32x16_bf16 v[50:65], v[138:141], v[156:159], v[50:65]
	ds_read_b64_tr_b16 v[156:157], v236 offset:0x2400
	ds_read_b64_tr_b16 v[158:159], v236 offset:0x2c00
	v_mfma_f32_32x32x16_bf16 v[50:65], v[142:145], v[194:197], v[50:65]
	ds_read_b64_tr_b16 v[194:195], v236 offset:0x3400
	ds_read_b64_tr_b16 v[196:197], v236 offset:0x3c00
	s_waitcnt lgkmcnt(0)
	v_mfma_f32_32x32x16_bf16 v[34:49], v[130:133], v[148:151], v[34:49]
	ds_read_b64_tr_b16 v[148:149], v236 offset:0x600
	ds_read_b64_tr_b16 v[150:151], v236 offset:0xe00
	v_mfma_f32_32x32x16_bf16 v[34:49], v[134:137], v[152:155], v[34:49]
	ds_read_b64_tr_b16 v[152:153], v236 offset:0x1600
	ds_read_b64_tr_b16 v[154:155], v236 offset:0x1e00
	v_mfma_f32_32x32x16_bf16 v[34:49], v[138:141], v[156:159], v[34:49]
	ds_read_b64_tr_b16 v[156:157], v236 offset:0x2600
	ds_read_b64_tr_b16 v[158:159], v236 offset:0x2e00
	v_mfma_f32_32x32x16_bf16 v[34:49], v[142:145], v[194:197], v[34:49]
	ds_read_b64_tr_b16 v[194:195], v236 offset:0x3600
	ds_read_b64_tr_b16 v[196:197], v236 offset:0x3e00
	s_waitcnt lgkmcnt(0)
	v_mfma_f32_32x32x16_bf16 v[18:33], v[130:133], v[148:151], v[18:33]
	s_barrier
	v_mfma_f32_32x32x16_bf16 v[18:33], v[134:137], v[152:155], v[18:33]
	v_mfma_f32_32x32x16_bf16 v[18:33], v[138:141], v[156:159], v[18:33]
	v_mfma_f32_32x32x16_bf16 v[18:33], v[142:145], v[194:197], v[18:33]
	s_branch .LBB0_562

.LBB0_584:
	v_add_f32_e32 v130, v247, v248
	v_fmac_f32_e32 v130, v237, v246
	v_add_f32_e32 v237, v146, v147
	s_add_i32 s51, s51, 2
	v_fmac_f32_e32 v237, v130, v250
	v_lshl_add_u64 v[216:217], v[216:217], 0, s[46:47]
	s_cmp_ge_u32 s2, s17
	v_lshl_add_u64 v[218:219], v[218:219], 0, s[46:47]
	s_cbranch_scc1 .LBB0_603
.LBB0_585:
	s_waitcnt vmcnt(0)
.LBB0_589:
	s_barrier
	ds_read_b128 v[194:197], v238
	ds_read_b128 v[198:201], v239
	ds_read_b128 v[202:205], v238 offset:8192
	ds_read_b128 v[206:209], v239 offset:8192
	s_waitcnt lgkmcnt(3)
	v_mfma_f32_32x32x16_bf16 v[146:161], v[194:197], v[162:165], 0
	ds_read_b128 v[194:197], v240
	s_waitcnt lgkmcnt(3)
	v_mfma_f32_32x32x16_bf16 v[146:161], v[198:201], v[166:169], v[146:161]
	s_cmp_lt_u32 s51, 5
	s_cbranch_scc1 .Lad2a_0
	s_mov_b64 s[100:101], 0xc0100
	s_mov_b32 m0, s42
	v_lshl_add_u64 v[250:251], v[222:223], 0, s[100:101]
	global_load_lds_dwordx4 v[250:251], off
.Lad2a_0:
	ds_read_b128 v[198:201], v240 offset:8192
	s_waitcnt lgkmcnt(3)
	v_mfma_f32_32x32x16_bf16 v[130:145], v[202:205], v[162:165], 0
	ds_read_b128 v[202:205], v241
	s_waitcnt lgkmcnt(3)
	v_mfma_f32_32x32x16_bf16 v[130:145], v[206:209], v[166:169], v[130:145]
	s_cmp_lt_u32 s51, 5
	s_cbranch_scc1 .Lad2a_1
	s_mov_b64 s[100:101], 0xe0100
	s_mov_b32 m0, s43
	v_lshl_add_u64 v[250:251], v[222:223], 0, s[100:101]
	global_load_lds_dwordx4 v[250:251], off
.Lad2a_1:
	ds_read_b128 v[206:209], v241 offset:8192
	s_waitcnt lgkmcnt(3)
	v_mfma_f32_32x32x16_bf16 v[146:161], v[194:197], v[170:173], v[146:161]
	ds_read_b128 v[194:197], v242
	s_waitcnt lgkmcnt(3)
	v_mfma_f32_32x32x16_bf16 v[130:145], v[198:201], v[170:173], v[130:145]
	s_cmp_lt_u32 s51, 5
	s_cbranch_scc1 .Lad2a_2
	s_mov_b64 s[100:101], 0xc0000
	s_add_i32 m0, s38, 0x10000
	v_lshl_add_u64 v[250:251], v[220:221], 0, s[100:101]
	global_load_lds_dwordx4 v[250:251], off
.Lad2a_2:
	ds_read_b128 v[198:201], v242 offset:8192
	s_waitcnt lgkmcnt(3)
	v_mfma_f32_32x32x16_bf16 v[146:161], v[202:205], v[174:177], v[146:161]
	ds_read_b128 v[202:205], v243
	s_waitcnt lgkmcnt(3)
	v_mfma_f32_32x32x16_bf16 v[130:145], v[206:209], v[174:177], v[130:145]
	s_cmp_lt_u32 s51, 5
	s_cbranch_scc1 .Lad2a_3
	s_mov_b64 s[100:101], 0xe0000
	s_add_i32 m0, s38, 0x12000
	v_lshl_add_u64 v[250:251], v[220:221], 0, s[100:101]
	global_load_lds_dwordx4 v[250:251], off
.Lad2a_3:
	ds_read_b128 v[206:209], v243 offset:8192
	s_waitcnt lgkmcnt(3)
	v_mfma_f32_32x32x16_bf16 v[146:161], v[194:197], v[178:181], v[146:161]
	ds_read_b128 v[194:197], v244
	s_waitcnt lgkmcnt(3)
	v_mfma_f32_32x32x16_bf16 v[130:145], v[198:201], v[178:181], v[130:145]
	s_cmp_lt_u32 s51, 5
	s_cbranch_scc1 .Lad2a_4
	s_mov_b64 s[100:101], 0xc0100
	s_add_i32 m0, s38, 0x14000
	v_lshl_add_u64 v[250:251], v[220:221], 0, s[100:101]
	global_load_lds_dwordx4 v[250:251], off
.Lad2a_4:
	ds_read_b128 v[198:201], v244 offset:8192
	s_waitcnt lgkmcnt(3)
	v_mfma_f32_32x32x16_bf16 v[146:161], v[202:205], v[182:185], v[146:161]
	ds_read_b128 v[202:205], v245
	s_waitcnt lgkmcnt(3)
	v_mfma_f32_32x32x16_bf16 v[130:145], v[206:209], v[182:185], v[130:145]
	s_cmp_lt_u32 s51, 5
	s_cbranch_scc1 .Lad2a_5
	s_mov_b64 s[100:101], 0xe0100
	s_add_i32 m0, s38, 0x16000
	v_lshl_add_u64 v[250:251], v[220:221], 0, s[100:101]
	global_load_lds_dwordx4 v[250:251], off
.Lad2a_5:
	ds_read_b128 v[206:209], v245 offset:8192
	s_waitcnt lgkmcnt(3)
	v_mfma_f32_32x32x16_bf16 v[146:161], v[194:197], v[186:189], v[146:161]
	s_waitcnt lgkmcnt(2)
	v_mfma_f32_32x32x16_bf16 v[130:145], v[198:201], v[186:189], v[130:145]
	s_waitcnt lgkmcnt(1)
	v_mfma_f32_32x32x16_bf16 v[146:161], v[202:205], v[190:193], v[146:161]
	s_waitcnt lgkmcnt(0)
	v_mfma_f32_32x32x16_bf16 v[130:145], v[206:209], v[190:193], v[130:145]
	s_nop 9
	v_max_f32_e32 v194, v147, v147
	v_max_f32_e32 v195, v146, v146
	v_max_f32_e32 v194, v195, v194
	v_max3_f32 v194, v194, v148, v149
	v_max3_f32 v194, v194, v150, v151
	v_max3_f32 v194, v194, v152, v153
	v_max3_f32 v194, v194, v154, v155
	v_max3_f32 v194, v194, v156, v157
	v_max3_f32 v194, v194, v158, v159
	v_max3_f32 v194, v194, v160, v161
	v_max3_f32 v194, v194, v130, v131
	v_max3_f32 v194, v194, v132, v133
	v_max3_f32 v194, v194, v134, v135
	v_max3_f32 v194, v194, v136, v137
	v_max3_f32 v194, v194, v138, v139
	v_max3_f32 v194, v194, v140, v141
	v_max3_f32 v194, v194, v142, v143
	v_max3_f32 v194, v194, v144, v145
	v_mov_b32_e32 v195, v194
	s_nop 1
	v_permlane32_swap_b32_e32 v194, v195
	v_max_f32_e32 v195, v195, v195
	v_max_f32_e32 v194, v194, v194
	v_max_f32_e32 v194, v194, v195
	v_sub_f32_e32 v195, v194, v249
	v_cmp_ge_f32_e32 vcc, s55, v195
	v_max_f32_e32 v195, v249, v249
	v_max_f32_e32 v220, v195, v194
	v_sub_f32_e32 v194, v249, v220
	v_mul_f32_e32 v194, 0x3e0293ee, v194
	v_exp_f32_e32 v194, v194
	s_cmp_eq_u64 vcc, exec
	s_cselect_b64 s[6:7], -1, 0
	v_cndmask_b32_e64 v246, v194, 1.0, s[6:7]
	v_cmp_gt_f32_e32 vcc, 1.0, v246
	s_cbranch_vccz .LBB0_593
	s_and_saveexec_b64 s[0:1], s[4:5]
	ds_write_b32 v225, v246 offset:128
	s_or_b64 exec, exec, s[0:1]
	s_waitcnt lgkmcnt(0)
	v_add_u32_e32 v194, s50, v210
	ds_read_b128 v[206:209], v194 offset:224
	ds_read_b128 v[202:205], v194 offset:192
	ds_read_b128 v[198:201], v194 offset:160
	ds_read_b128 v[194:197], v194 offset:128
	s_waitcnt lgkmcnt(0)
	v_pk_mul_f32 v[14:15], v[14:15], v[206:207]
	s_waitcnt lgkmcnt(2)
	v_pk_mul_f32 v[10:11], v[10:11], v[202:203]
	s_waitcnt lgkmcnt(1)
	v_pk_mul_f32 v[6:7], v[6:7], v[198:199]
	v_pk_mul_f32 v[16:17], v[16:17], v[208:209]
	v_pk_mul_f32 v[12:13], v[12:13], v[204:205]
	v_pk_mul_f32 v[8:9], v[8:9], v[200:201]
	s_waitcnt lgkmcnt(0)
	v_pk_mul_f32 v[4:5], v[4:5], v[196:197]
	v_pk_mul_f32 v[2:3], v[2:3], v[194:195]
	v_pk_mul_f32 v[30:31], v[30:31], v[206:207]
	v_pk_mul_f32 v[26:27], v[26:27], v[202:203]
	v_pk_mul_f32 v[22:23], v[22:23], v[198:199]
	v_pk_mul_f32 v[32:33], v[32:33], v[208:209]
	v_pk_mul_f32 v[28:29], v[28:29], v[204:205]
	v_pk_mul_f32 v[24:25], v[24:25], v[200:201]
	v_pk_mul_f32 v[20:21], v[20:21], v[196:197]
	v_pk_mul_f32 v[18:19], v[18:19], v[194:195]
	v_pk_mul_f32 v[46:47], v[46:47], v[206:207]
	v_pk_mul_f32 v[42:43], v[42:43], v[202:203]
	v_pk_mul_f32 v[38:39], v[38:39], v[198:199]
	v_pk_mul_f32 v[48:49], v[48:49], v[208:209]
	v_pk_mul_f32 v[44:45], v[44:45], v[204:205]
	v_pk_mul_f32 v[40:41], v[40:41], v[200:201]
	v_pk_mul_f32 v[36:37], v[36:37], v[196:197]
	v_pk_mul_f32 v[34:35], v[34:35], v[194:195]
	v_pk_mul_f32 v[62:63], v[62:63], v[206:207]
	v_pk_mul_f32 v[58:59], v[58:59], v[202:203]
	v_pk_mul_f32 v[54:55], v[54:55], v[198:199]
	v_pk_mul_f32 v[64:65], v[64:65], v[208:209]
	v_pk_mul_f32 v[60:61], v[60:61], v[204:205]
	v_pk_mul_f32 v[56:57], v[56:57], v[200:201]
	v_pk_mul_f32 v[52:53], v[52:53], v[196:197]
	v_pk_mul_f32 v[50:51], v[50:51], v[194:195]
	v_pk_mul_f32 v[78:79], v[78:79], v[206:207]
	v_pk_mul_f32 v[74:75], v[74:75], v[202:203]
	v_pk_mul_f32 v[70:71], v[70:71], v[198:199]
	v_pk_mul_f32 v[80:81], v[80:81], v[208:209]
	v_pk_mul_f32 v[76:77], v[76:77], v[204:205]
	v_pk_mul_f32 v[72:73], v[72:73], v[200:201]
	v_pk_mul_f32 v[68:69], v[68:69], v[196:197]
	v_pk_mul_f32 v[66:67], v[66:67], v[194:195]
	v_pk_mul_f32 v[94:95], v[94:95], v[206:207]
	v_pk_mul_f32 v[90:91], v[90:91], v[202:203]
	v_pk_mul_f32 v[86:87], v[86:87], v[198:199]
	v_pk_mul_f32 v[96:97], v[96:97], v[208:209]
	v_pk_mul_f32 v[92:93], v[92:93], v[204:205]
	v_pk_mul_f32 v[88:89], v[88:89], v[200:201]
	v_pk_mul_f32 v[84:85], v[84:85], v[196:197]
	v_pk_mul_f32 v[82:83], v[82:83], v[194:195]
	v_pk_mul_f32 v[110:111], v[110:111], v[206:207]
	v_pk_mul_f32 v[106:107], v[106:107], v[202:203]
	v_pk_mul_f32 v[102:103], v[102:103], v[198:199]
	v_pk_mul_f32 v[112:113], v[112:113], v[208:209]
	v_pk_mul_f32 v[108:109], v[108:109], v[204:205]
	v_pk_mul_f32 v[104:105], v[104:105], v[200:201]
	v_pk_mul_f32 v[100:101], v[100:101], v[196:197]
	v_pk_mul_f32 v[98:99], v[98:99], v[194:195]
	v_pk_mul_f32 v[126:127], v[126:127], v[206:207]
	v_pk_mul_f32 v[122:123], v[122:123], v[202:203]
	v_pk_mul_f32 v[118:119], v[118:119], v[198:199]
	v_pk_mul_f32 v[128:129], v[128:129], v[208:209]
	v_pk_mul_f32 v[124:125], v[124:125], v[204:205]
	v_pk_mul_f32 v[120:121], v[120:121], v[200:201]
	v_pk_mul_f32 v[116:117], v[116:117], v[196:197]
	v_pk_mul_f32 v[114:115], v[114:115], v[194:195]
.LBB0_593:
	v_cndmask_b32_e64 v249, v220, v249, s[6:7]
	v_mul_f32_e32 v194, 0xbe0293ee, v249
	v_fmamk_f32 v146, v146, 0x3e0293ee, v194
	v_fmamk_f32 v147, v147, 0x3e0293ee, v194
	v_fmamk_f32 v148, v148, 0x3e0293ee, v194
	v_fmamk_f32 v149, v149, 0x3e0293ee, v194
	v_fmamk_f32 v150, v150, 0x3e0293ee, v194
	v_fmamk_f32 v151, v151, 0x3e0293ee, v194
	v_fmamk_f32 v152, v152, 0x3e0293ee, v194
	v_fmamk_f32 v153, v153, 0x3e0293ee, v194
	v_fmamk_f32 v154, v154, 0x3e0293ee, v194
	v_fmamk_f32 v155, v155, 0x3e0293ee, v194
	v_fmamk_f32 v156, v156, 0x3e0293ee, v194
	v_fmamk_f32 v157, v157, 0x3e0293ee, v194
	v_fmamk_f32 v158, v158, 0x3e0293ee, v194
	v_fmamk_f32 v159, v159, 0x3e0293ee, v194
	v_fmamk_f32 v160, v160, 0x3e0293ee, v194
	v_fmamk_f32 v161, v161, 0x3e0293ee, v194
	v_fmamk_f32 v130, v130, 0x3e0293ee, v194
	v_fmamk_f32 v131, v131, 0x3e0293ee, v194
	v_fmamk_f32 v132, v132, 0x3e0293ee, v194
	v_fmamk_f32 v133, v133, 0x3e0293ee, v194
	v_fmamk_f32 v134, v134, 0x3e0293ee, v194
	v_fmamk_f32 v135, v135, 0x3e0293ee, v194
	v_fmamk_f32 v136, v136, 0x3e0293ee, v194
	v_fmamk_f32 v137, v137, 0x3e0293ee, v194
	v_fmamk_f32 v138, v138, 0x3e0293ee, v194
	v_fmamk_f32 v139, v139, 0x3e0293ee, v194
	v_fmamk_f32 v140, v140, 0x3e0293ee, v194
	v_fmamk_f32 v141, v141, 0x3e0293ee, v194
	v_fmamk_f32 v142, v142, 0x3e0293ee, v194
	v_fmamk_f32 v143, v143, 0x3e0293ee, v194
	v_fmamk_f32 v144, v144, 0x3e0293ee, v194
	v_fmac_f32_e32 v194, 0x3e0293ee, v145
	v_exp_f32_e32 v145, v146
	v_exp_f32_e32 v146, v147
	v_exp_f32_e32 v147, v148
	v_exp_f32_e32 v148, v149
	v_exp_f32_e32 v149, v150
	v_exp_f32_e32 v150, v151
	v_exp_f32_e32 v151, v152
	v_exp_f32_e32 v152, v153
	v_exp_f32_e32 v153, v154
	v_exp_f32_e32 v154, v155
	v_exp_f32_e32 v155, v156
	v_exp_f32_e32 v156, v157
	v_exp_f32_e32 v157, v158
	v_exp_f32_e32 v158, v159
	v_exp_f32_e32 v159, v160
	v_exp_f32_e32 v160, v161
	v_exp_f32_e32 v161, v130
	v_add_f32_e32 v130, 0, v145
	v_add_f32_e32 v130, v146, v130
	v_add_f32_e32 v130, v147, v130
	v_add_f32_e32 v130, v148, v130
	v_add_f32_e32 v130, v149, v130
	v_add_f32_e32 v130, v150, v130
	v_add_f32_e32 v130, v151, v130
	v_add_f32_e32 v130, v152, v130
	v_add_f32_e32 v130, v153, v130
	v_add_f32_e32 v130, v154, v130
	v_add_f32_e32 v130, v155, v130
	v_add_f32_e32 v130, v156, v130
	v_add_f32_e32 v130, v157, v130
	v_exp_f32_e32 v195, v131
	v_add_f32_e32 v130, v158, v130
	v_exp_f32_e32 v196, v132
	v_add_f32_e32 v130, v159, v130
	v_exp_f32_e32 v197, v133
	v_add_f32_e32 v130, v160, v130
	v_exp_f32_e32 v198, v134
	v_add_f32_e32 v130, v161, v130
	v_exp_f32_e32 v199, v135
	v_add_f32_e32 v130, v195, v130
	v_exp_f32_e32 v200, v136
	v_add_f32_e32 v130, v196, v130
	v_exp_f32_e32 v201, v137
	v_add_f32_e32 v130, v197, v130
	v_exp_f32_e32 v202, v138
	v_add_f32_e32 v130, v198, v130
	v_exp_f32_e32 v203, v139
	v_add_f32_e32 v130, v199, v130
	v_exp_f32_e32 v204, v140
	v_add_f32_e32 v130, v200, v130
	v_exp_f32_e32 v205, v141
	v_add_f32_e32 v130, v201, v130
	v_exp_f32_e32 v206, v142
	v_add_f32_e32 v130, v202, v130
	v_exp_f32_e32 v207, v143
	v_add_f32_e32 v130, v203, v130
	v_exp_f32_e32 v208, v144
	v_add_f32_e32 v130, v204, v130
	v_exp_f32_e32 v194, v194
	v_add_f32_e32 v130, v205, v130
	v_add_f32_e32 v130, v206, v130
	v_add_f32_e32 v130, v207, v130
	v_add_f32_e32 v130, v208, v130
	v_add_f32_e32 v247, v194, v130
	v_mov_b32_e32 v248, v247
	s_nop 1
	v_permlane32_swap_b32_e32 v247, v248
	v_cvt_pk_bf16_f32 v130, v145, v146
	v_cvt_pk_bf16_f32 v131, v147, v148
	v_cvt_pk_bf16_f32 v132, v149, v150
	v_cvt_pk_bf16_f32 v133, v151, v152
	v_cvt_pk_bf16_f32 v134, v153, v154
	v_cvt_pk_bf16_f32 v135, v155, v156
	v_cvt_pk_bf16_f32 v136, v157, v158
	v_cvt_pk_bf16_f32 v137, v159, v160
	v_cvt_pk_bf16_f32 v138, v161, v195
	v_cvt_pk_bf16_f32 v139, v196, v197
	v_cvt_pk_bf16_f32 v140, v198, v199
	v_cvt_pk_bf16_f32 v141, v200, v201
	v_cvt_pk_bf16_f32 v142, v202, v203
	v_cvt_pk_bf16_f32 v143, v204, v205
	v_cvt_pk_bf16_f32 v144, v206, v207
	v_cvt_pk_bf16_f32 v145, v208, v194
	s_nop 0
	v_permlane32_swap_b32_e32 v130, v132
	v_permlane32_swap_b32_e32 v131, v133
	v_permlane32_swap_b32_e32 v134, v136
	v_permlane32_swap_b32_e32 v135, v137
	v_permlane32_swap_b32_e32 v138, v140
	v_permlane32_swap_b32_e32 v139, v141
	v_permlane32_swap_b32_e32 v142, v144
	v_permlane32_swap_b32_e32 v143, v145
	ds_read_b64_tr_b16 v[146:147], v224 offset:0
	ds_read_b64_tr_b16 v[148:149], v224 offset:0x800
	ds_read_b64_tr_b16 v[150:151], v224 offset:0x1000
	ds_read_b64_tr_b16 v[152:153], v224 offset:0x1800
	ds_read_b64_tr_b16 v[154:155], v224 offset:0x2000
	ds_read_b64_tr_b16 v[156:157], v224 offset:0x2800
	ds_read_b64_tr_b16 v[158:159], v224 offset:0x3000
	ds_read_b64_tr_b16 v[160:161], v224 offset:0x3800
	s_waitcnt lgkmcnt(0)
	s_nop 0
	v_mfma_f32_32x32x16_bf16 v[2:17], v[130:133], v[146:149], v[2:17]
	ds_read_b64_tr_b16 v[146:147], v224 offset:0x200
	ds_read_b64_tr_b16 v[148:149], v224 offset:0xa00
	v_mfma_f32_32x32x16_bf16 v[2:17], v[134:137], v[150:153], v[2:17]
	ds_read_b64_tr_b16 v[150:151], v224 offset:0x1200
	ds_read_b64_tr_b16 v[152:153], v224 offset:0x1a00
	v_mfma_f32_32x32x16_bf16 v[2:17], v[138:141], v[154:157], v[2:17]
	ds_read_b64_tr_b16 v[154:155], v224 offset:0x2200
	ds_read_b64_tr_b16 v[156:157], v224 offset:0x2a00
	v_mfma_f32_32x32x16_bf16 v[2:17], v[142:145], v[158:161], v[2:17]
	ds_read_b64_tr_b16 v[158:159], v224 offset:0x3200
	ds_read_b64_tr_b16 v[160:161], v224 offset:0x3a00
	s_waitcnt lgkmcnt(0)
	v_mfma_f32_32x32x16_bf16 v[18:33], v[130:133], v[146:149], v[18:33]
	ds_read_b64_tr_b16 v[146:147], v224 offset:0x400
	ds_read_b64_tr_b16 v[148:149], v224 offset:0xc00
	v_mfma_f32_32x32x16_bf16 v[18:33], v[134:137], v[150:153], v[18:33]
	ds_read_b64_tr_b16 v[150:151], v224 offset:0x1400
	ds_read_b64_tr_b16 v[152:153], v224 offset:0x1c00
	v_mfma_f32_32x32x16_bf16 v[18:33], v[138:141], v[154:157], v[18:33]
	ds_read_b64_tr_b16 v[154:155], v224 offset:0x2400
	ds_read_b64_tr_b16 v[156:157], v224 offset:0x2c00
	v_mfma_f32_32x32x16_bf16 v[18:33], v[142:145], v[158:161], v[18:33]
	ds_read_b64_tr_b16 v[158:159], v224 offset:0x3400
	ds_read_b64_tr_b16 v[160:161], v224 offset:0x3c00
	s_waitcnt lgkmcnt(0)
	v_mfma_f32_32x32x16_bf16 v[34:49], v[130:133], v[146:149], v[34:49]
	ds_read_b64_tr_b16 v[146:147], v224 offset:0x600
	ds_read_b64_tr_b16 v[148:149], v224 offset:0xe00
	v_mfma_f32_32x32x16_bf16 v[34:49], v[134:137], v[150:153], v[34:49]
	ds_read_b64_tr_b16 v[150:151], v224 offset:0x1600
	ds_read_b64_tr_b16 v[152:153], v224 offset:0x1e00
	v_mfma_f32_32x32x16_bf16 v[34:49], v[138:141], v[154:157], v[34:49]
	ds_read_b64_tr_b16 v[154:155], v224 offset:0x2600
	ds_read_b64_tr_b16 v[156:157], v224 offset:0x2e00
	v_mfma_f32_32x32x16_bf16 v[34:49], v[142:145], v[158:161], v[34:49]
	ds_read_b64_tr_b16 v[158:159], v224 offset:0x3600
	ds_read_b64_tr_b16 v[160:161], v224 offset:0x3e00
	s_waitcnt lgkmcnt(0)
	v_mfma_f32_32x32x16_bf16 v[50:65], v[130:133], v[146:149], v[50:65]
	ds_read_b64_tr_b16 v[146:147], v234 offset:0
	ds_read_b64_tr_b16 v[148:149], v234 offset:0x800
	v_mfma_f32_32x32x16_bf16 v[50:65], v[134:137], v[150:153], v[50:65]
	ds_read_b64_tr_b16 v[150:151], v234 offset:0x1000
	ds_read_b64_tr_b16 v[152:153], v234 offset:0x1800
	v_mfma_f32_32x32x16_bf16 v[50:65], v[138:141], v[154:157], v[50:65]
	ds_read_b64_tr_b16 v[154:155], v234 offset:0x2000
	ds_read_b64_tr_b16 v[156:157], v234 offset:0x2800
	v_mfma_f32_32x32x16_bf16 v[50:65], v[142:145], v[158:161], v[50:65]
	ds_read_b64_tr_b16 v[158:159], v234 offset:0x3000
	ds_read_b64_tr_b16 v[160:161], v234 offset:0x3800
	s_waitcnt lgkmcnt(0)
	v_mfma_f32_32x32x16_bf16 v[66:81], v[130:133], v[146:149], v[66:81]
	ds_read_b64_tr_b16 v[146:147], v234 offset:0x200
	ds_read_b64_tr_b16 v[148:149], v234 offset:0xa00
	v_mfma_f32_32x32x16_bf16 v[66:81], v[134:137], v[150:153], v[66:81]
	ds_read_b64_tr_b16 v[150:151], v234 offset:0x1200
	ds_read_b64_tr_b16 v[152:153], v234 offset:0x1a00
	v_mfma_f32_32x32x16_bf16 v[66:81], v[138:141], v[154:157], v[66:81]
	ds_read_b64_tr_b16 v[154:155], v234 offset:0x2200
	ds_read_b64_tr_b16 v[156:157], v234 offset:0x2a00
	v_mfma_f32_32x32x16_bf16 v[66:81], v[142:145], v[158:161], v[66:81]
	ds_read_b64_tr_b16 v[158:159], v234 offset:0x3200
	ds_read_b64_tr_b16 v[160:161], v234 offset:0x3a00
	s_waitcnt lgkmcnt(0)
	v_mfma_f32_32x32x16_bf16 v[82:97], v[130:133], v[146:149], v[82:97]
	ds_read_b64_tr_b16 v[146:147], v234 offset:0x400
	ds_read_b64_tr_b16 v[148:149], v234 offset:0xc00
	v_mfma_f32_32x32x16_bf16 v[82:97], v[134:137], v[150:153], v[82:97]
	ds_read_b64_tr_b16 v[150:151], v234 offset:0x1400
	ds_read_b64_tr_b16 v[152:153], v234 offset:0x1c00
	v_mfma_f32_32x32x16_bf16 v[82:97], v[138:141], v[154:157], v[82:97]
	ds_read_b64_tr_b16 v[154:155], v234 offset:0x2400
	ds_read_b64_tr_b16 v[156:157], v234 offset:0x2c00
	v_mfma_f32_32x32x16_bf16 v[82:97], v[142:145], v[158:161], v[82:97]
	ds_read_b64_tr_b16 v[158:159], v234 offset:0x3400
	ds_read_b64_tr_b16 v[160:161], v234 offset:0x3c00
	s_waitcnt lgkmcnt(0)
	v_mfma_f32_32x32x16_bf16 v[98:113], v[130:133], v[146:149], v[98:113]
	ds_read_b64_tr_b16 v[146:147], v234 offset:0x600
	ds_read_b64_tr_b16 v[148:149], v234 offset:0xe00
	v_mfma_f32_32x32x16_bf16 v[98:113], v[134:137], v[150:153], v[98:113]
	ds_read_b64_tr_b16 v[150:151], v234 offset:0x1600
	ds_read_b64_tr_b16 v[152:153], v234 offset:0x1e00
	v_mfma_f32_32x32x16_bf16 v[98:113], v[138:141], v[154:157], v[98:113]
	ds_read_b64_tr_b16 v[154:155], v234 offset:0x2600
	ds_read_b64_tr_b16 v[156:157], v234 offset:0x2e00
	v_mfma_f32_32x32x16_bf16 v[98:113], v[142:145], v[158:161], v[98:113]
	ds_read_b64_tr_b16 v[158:159], v234 offset:0x3600
	ds_read_b64_tr_b16 v[160:161], v234 offset:0x3e00
	s_waitcnt lgkmcnt(0)
	v_mfma_f32_32x32x16_bf16 v[114:129], v[130:133], v[146:149], v[114:129]
	s_barrier
	v_mfma_f32_32x32x16_bf16 v[114:129], v[134:137], v[150:153], v[114:129]
	v_mfma_f32_32x32x16_bf16 v[114:129], v[138:141], v[154:157], v[114:129]
	v_mfma_f32_32x32x16_bf16 v[114:129], v[142:145], v[158:161], v[114:129]
	s_add_i32 s2, s51, -1
	v_lshl_add_u64 v[222:223], v[216:217], 0, s[44:45]
	v_lshl_add_u64 v[220:221], v[218:219], 0, s[44:45]
	s_waitcnt vmcnt(0)
.LBB0_595:
.LBB0_597:
	s_barrier
	ds_read_b128 v[194:197], v238 offset:16384
	ds_read_b128 v[198:201], v239 offset:16384
	ds_read_b128 v[202:205], v238 offset:24576
	ds_read_b128 v[206:209], v239 offset:24576
	s_waitcnt lgkmcnt(3)
	v_mfma_f32_32x32x16_bf16 v[146:161], v[194:197], v[162:165], 0
	ds_read_b128 v[194:197], v240 offset:16384
	s_waitcnt lgkmcnt(3)
	v_mfma_f32_32x32x16_bf16 v[146:161], v[198:201], v[166:169], v[146:161]
	s_cmp_ge_u32 s2, s17
	s_cbranch_scc1 .Lad2b_0
	s_mov_b64 s[100:101], 0x80100
	s_mov_b32 m0, s38
	v_lshl_add_u64 v[250:251], v[222:223], 0, s[100:101]
	global_load_lds_dwordx4 v[250:251], off
.Lad2b_0:
	ds_read_b128 v[198:201], v240 offset:24576
	s_waitcnt lgkmcnt(3)
	v_mfma_f32_32x32x16_bf16 v[130:145], v[202:205], v[162:165], 0
	ds_read_b128 v[202:205], v241 offset:16384
	s_waitcnt lgkmcnt(3)
	v_mfma_f32_32x32x16_bf16 v[130:145], v[206:209], v[166:169], v[130:145]
	s_cmp_ge_u32 s2, s17
	s_cbranch_scc1 .Lad2b_1
	s_mov_b64 s[100:101], 0xa0100
	s_mov_b32 m0, s39
	v_lshl_add_u64 v[250:251], v[222:223], 0, s[100:101]
	global_load_lds_dwordx4 v[250:251], off
.Lad2b_1:
	ds_read_b128 v[206:209], v241 offset:24576
	s_waitcnt lgkmcnt(3)
	v_mfma_f32_32x32x16_bf16 v[146:161], v[194:197], v[170:173], v[146:161]
	ds_read_b128 v[194:197], v242 offset:16384
	s_waitcnt lgkmcnt(3)
	v_mfma_f32_32x32x16_bf16 v[130:145], v[198:201], v[170:173], v[130:145]
	s_cmp_ge_u32 s2, s17
	s_cbranch_scc1 .Lad2b_2
	s_mov_b64 s[100:101], 0x80000
	s_mov_b32 m0, s40
	v_lshl_add_u64 v[250:251], v[220:221], 0, s[100:101]
	global_load_lds_dwordx4 v[250:251], off
.Lad2b_2:
	ds_read_b128 v[198:201], v242 offset:24576
	s_waitcnt lgkmcnt(3)
	v_mfma_f32_32x32x16_bf16 v[146:161], v[202:205], v[174:177], v[146:161]
	ds_read_b128 v[202:205], v243 offset:16384
	s_waitcnt lgkmcnt(3)
	v_mfma_f32_32x32x16_bf16 v[130:145], v[206:209], v[174:177], v[130:145]
	s_cmp_ge_u32 s2, s17
	s_cbranch_scc1 .Lad2b_3
	s_mov_b64 s[100:101], 0xa0000
	s_mov_b32 m0, s36
	v_lshl_add_u64 v[250:251], v[220:221], 0, s[100:101]
	global_load_lds_dwordx4 v[250:251], off
.Lad2b_3:
	ds_read_b128 v[206:209], v243 offset:24576
	s_waitcnt lgkmcnt(3)
	v_mfma_f32_32x32x16_bf16 v[146:161], v[194:197], v[178:181], v[146:161]
	ds_read_b128 v[194:197], v244 offset:16384
	s_waitcnt lgkmcnt(3)
	v_mfma_f32_32x32x16_bf16 v[130:145], v[198:201], v[178:181], v[130:145]
	s_cmp_ge_u32 s2, s17
	s_cbranch_scc1 .Lad2b_4
	s_mov_b64 s[100:101], 0x80100
	s_mov_b32 m0, s37
	v_lshl_add_u64 v[250:251], v[220:221], 0, s[100:101]
	global_load_lds_dwordx4 v[250:251], off
.Lad2b_4:
	ds_read_b128 v[198:201], v244 offset:24576
	s_waitcnt lgkmcnt(3)
	v_mfma_f32_32x32x16_bf16 v[146:161], v[202:205], v[182:185], v[146:161]
	ds_read_b128 v[202:205], v245 offset:16384
	s_waitcnt lgkmcnt(3)
	v_mfma_f32_32x32x16_bf16 v[130:145], v[206:209], v[182:185], v[130:145]
	s_cmp_ge_u32 s2, s17
	s_cbranch_scc1 .Lad2b_5
	s_mov_b64 s[100:101], 0xa0100
	s_mov_b32 m0, s41
	v_lshl_add_u64 v[250:251], v[220:221], 0, s[100:101]
	global_load_lds_dwordx4 v[250:251], off
.Lad2b_5:
	ds_read_b128 v[206:209], v245 offset:24576
	s_waitcnt lgkmcnt(3)
	v_mfma_f32_32x32x16_bf16 v[146:161], v[194:197], v[186:189], v[146:161]
	s_waitcnt lgkmcnt(2)
	v_mfma_f32_32x32x16_bf16 v[130:145], v[198:201], v[186:189], v[130:145]
	s_waitcnt lgkmcnt(1)
	v_mfma_f32_32x32x16_bf16 v[146:161], v[202:205], v[190:193], v[146:161]
	s_waitcnt lgkmcnt(0)
	v_mfma_f32_32x32x16_bf16 v[130:145], v[206:209], v[190:193], v[130:145]
	s_nop 9
	v_max_f32_e32 v194, v147, v147
	v_max_f32_e32 v195, v146, v146
	v_max_f32_e32 v194, v195, v194
	v_max3_f32 v194, v194, v148, v149
	v_max3_f32 v194, v194, v150, v151
	v_max3_f32 v194, v194, v152, v153
	v_max3_f32 v194, v194, v154, v155
	v_max3_f32 v194, v194, v156, v157
	v_max3_f32 v194, v194, v158, v159
	v_max3_f32 v194, v194, v160, v161
	v_max3_f32 v194, v194, v130, v131
	v_max3_f32 v194, v194, v132, v133
	v_max3_f32 v194, v194, v134, v135
	v_max3_f32 v194, v194, v136, v137
	v_max3_f32 v194, v194, v138, v139
	v_max3_f32 v194, v194, v140, v141
	v_max3_f32 v194, v194, v142, v143
	v_max3_f32 v194, v194, v144, v145
	v_mov_b32_e32 v195, v194
	s_nop 1
	v_permlane32_swap_b32_e32 v194, v195
	v_max_f32_e32 v195, v195, v195
	v_max_f32_e32 v194, v194, v194
	v_max_f32_e32 v194, v194, v195
	v_sub_f32_e32 v195, v194, v249
	v_cmp_ge_f32_e32 vcc, s55, v195
	v_max_f32_e32 v195, v249, v249
	v_max_f32_e32 v251, v195, v194
	v_sub_f32_e32 v194, v249, v251
	v_mul_f32_e32 v194, 0x3e0293ee, v194
	v_exp_f32_e32 v194, v194
	s_cmp_eq_u64 vcc, exec
	s_cselect_b64 s[6:7], -1, 0
	v_cndmask_b32_e64 v250, v194, 1.0, s[6:7]
	v_cmp_gt_f32_e32 vcc, 1.0, v250
	s_cbranch_vccz .LBB0_601
	s_and_saveexec_b64 s[0:1], s[4:5]
	ds_write_b32 v225, v250 offset:128
	s_or_b64 exec, exec, s[0:1]
	s_waitcnt lgkmcnt(0)
	v_add_u32_e32 v194, s50, v210
	ds_read_b128 v[206:209], v194 offset:224
	ds_read_b128 v[202:205], v194 offset:192
	ds_read_b128 v[198:201], v194 offset:160
	ds_read_b128 v[194:197], v194 offset:128
	s_waitcnt lgkmcnt(0)
	v_pk_mul_f32 v[14:15], v[14:15], v[206:207]
	v_pk_mul_f32 v[10:11], v[10:11], v[202:203]
	v_pk_mul_f32 v[6:7], v[6:7], v[198:199]
	v_pk_mul_f32 v[16:17], v[16:17], v[208:209]
	v_pk_mul_f32 v[12:13], v[12:13], v[204:205]
	v_pk_mul_f32 v[8:9], v[8:9], v[200:201]
	v_pk_mul_f32 v[4:5], v[4:5], v[196:197]
	v_pk_mul_f32 v[2:3], v[2:3], v[194:195]
	v_pk_mul_f32 v[30:31], v[30:31], v[206:207]
	v_pk_mul_f32 v[26:27], v[26:27], v[202:203]
	v_pk_mul_f32 v[22:23], v[22:23], v[198:199]
	v_pk_mul_f32 v[32:33], v[32:33], v[208:209]
	v_pk_mul_f32 v[28:29], v[28:29], v[204:205]
	v_pk_mul_f32 v[24:25], v[24:25], v[200:201]
	v_pk_mul_f32 v[20:21], v[20:21], v[196:197]
	v_pk_mul_f32 v[18:19], v[18:19], v[194:195]
	v_pk_mul_f32 v[46:47], v[46:47], v[206:207]
	v_pk_mul_f32 v[42:43], v[42:43], v[202:203]
	v_pk_mul_f32 v[38:39], v[38:39], v[198:199]
	v_pk_mul_f32 v[48:49], v[48:49], v[208:209]
	v_pk_mul_f32 v[44:45], v[44:45], v[204:205]
	v_pk_mul_f32 v[40:41], v[40:41], v[200:201]
	v_pk_mul_f32 v[36:37], v[36:37], v[196:197]
	v_pk_mul_f32 v[34:35], v[34:35], v[194:195]
	v_pk_mul_f32 v[62:63], v[62:63], v[206:207]
	v_pk_mul_f32 v[58:59], v[58:59], v[202:203]
	v_pk_mul_f32 v[54:55], v[54:55], v[198:199]
	v_pk_mul_f32 v[64:65], v[64:65], v[208:209]
	v_pk_mul_f32 v[60:61], v[60:61], v[204:205]
	v_pk_mul_f32 v[56:57], v[56:57], v[200:201]
	v_pk_mul_f32 v[52:53], v[52:53], v[196:197]
	v_pk_mul_f32 v[50:51], v[50:51], v[194:195]
	v_pk_mul_f32 v[78:79], v[78:79], v[206:207]
	v_pk_mul_f32 v[74:75], v[74:75], v[202:203]
	v_pk_mul_f32 v[70:71], v[70:71], v[198:199]
	v_pk_mul_f32 v[80:81], v[80:81], v[208:209]
	v_pk_mul_f32 v[76:77], v[76:77], v[204:205]
	v_pk_mul_f32 v[72:73], v[72:73], v[200:201]
	v_pk_mul_f32 v[68:69], v[68:69], v[196:197]
	v_pk_mul_f32 v[66:67], v[66:67], v[194:195]
	v_pk_mul_f32 v[94:95], v[94:95], v[206:207]
	v_pk_mul_f32 v[90:91], v[90:91], v[202:203]
	v_pk_mul_f32 v[86:87], v[86:87], v[198:199]
	v_pk_mul_f32 v[96:97], v[96:97], v[208:209]
	v_pk_mul_f32 v[92:93], v[92:93], v[204:205]
	v_pk_mul_f32 v[88:89], v[88:89], v[200:201]
	v_pk_mul_f32 v[84:85], v[84:85], v[196:197]
	v_pk_mul_f32 v[82:83], v[82:83], v[194:195]
	v_pk_mul_f32 v[110:111], v[110:111], v[206:207]
	v_pk_mul_f32 v[106:107], v[106:107], v[202:203]
	v_pk_mul_f32 v[102:103], v[102:103], v[198:199]
	v_pk_mul_f32 v[112:113], v[112:113], v[208:209]
	v_pk_mul_f32 v[108:109], v[108:109], v[204:205]
	v_pk_mul_f32 v[104:105], v[104:105], v[200:201]
	v_pk_mul_f32 v[100:101], v[100:101], v[196:197]
	v_pk_mul_f32 v[98:99], v[98:99], v[194:195]
	v_pk_mul_f32 v[126:127], v[126:127], v[206:207]
	v_pk_mul_f32 v[122:123], v[122:123], v[202:203]
	v_pk_mul_f32 v[118:119], v[118:119], v[198:199]
	v_pk_mul_f32 v[128:129], v[128:129], v[208:209]
	v_pk_mul_f32 v[124:125], v[124:125], v[204:205]
	v_pk_mul_f32 v[120:121], v[120:121], v[200:201]
	v_pk_mul_f32 v[116:117], v[116:117], v[196:197]
	v_pk_mul_f32 v[114:115], v[114:115], v[194:195]
.LBB0_601:
	v_cndmask_b32_e64 v249, v251, v249, s[6:7]
	v_mul_f32_e32 v194, 0xbe0293ee, v249
	v_fmamk_f32 v146, v146, 0x3e0293ee, v194
	v_fmamk_f32 v147, v147, 0x3e0293ee, v194
	v_fmamk_f32 v148, v148, 0x3e0293ee, v194
	v_fmamk_f32 v149, v149, 0x3e0293ee, v194
	v_fmamk_f32 v150, v150, 0x3e0293ee, v194
	v_fmamk_f32 v151, v151, 0x3e0293ee, v194
	v_fmamk_f32 v152, v152, 0x3e0293ee, v194
	v_fmamk_f32 v153, v153, 0x3e0293ee, v194
	v_fmamk_f32 v154, v154, 0x3e0293ee, v194
	v_fmamk_f32 v155, v155, 0x3e0293ee, v194
	v_fmamk_f32 v156, v156, 0x3e0293ee, v194
	v_fmamk_f32 v157, v157, 0x3e0293ee, v194
	v_fmamk_f32 v158, v158, 0x3e0293ee, v194
	v_fmamk_f32 v159, v159, 0x3e0293ee, v194
	v_fmamk_f32 v160, v160, 0x3e0293ee, v194
	v_fmamk_f32 v161, v161, 0x3e0293ee, v194
	v_fmamk_f32 v130, v130, 0x3e0293ee, v194
	v_fmamk_f32 v131, v131, 0x3e0293ee, v194
	v_fmamk_f32 v132, v132, 0x3e0293ee, v194
	v_fmamk_f32 v133, v133, 0x3e0293ee, v194
	v_fmamk_f32 v134, v134, 0x3e0293ee, v194
	v_fmamk_f32 v135, v135, 0x3e0293ee, v194
	v_fmamk_f32 v136, v136, 0x3e0293ee, v194
	v_fmamk_f32 v137, v137, 0x3e0293ee, v194
	v_fmamk_f32 v138, v138, 0x3e0293ee, v194
	v_fmamk_f32 v139, v139, 0x3e0293ee, v194
	v_fmamk_f32 v140, v140, 0x3e0293ee, v194
	v_fmamk_f32 v141, v141, 0x3e0293ee, v194
	v_fmamk_f32 v142, v142, 0x3e0293ee, v194
	v_fmamk_f32 v143, v143, 0x3e0293ee, v194
	v_fmamk_f32 v144, v144, 0x3e0293ee, v194
	v_fmac_f32_e32 v194, 0x3e0293ee, v145
	v_exp_f32_e32 v145, v146
	v_exp_f32_e32 v195, v147
	v_exp_f32_e32 v148, v148
	v_exp_f32_e32 v149, v149
	v_exp_f32_e32 v150, v150
	v_exp_f32_e32 v196, v130
	v_add_f32_e32 v130, 0, v145
	v_exp_f32_e32 v151, v151
	v_add_f32_e32 v130, v195, v130
	v_exp_f32_e32 v152, v152
	v_add_f32_e32 v130, v148, v130
	v_exp_f32_e32 v153, v153
	v_add_f32_e32 v130, v149, v130
	v_exp_f32_e32 v154, v154
	v_add_f32_e32 v130, v150, v130
	v_exp_f32_e32 v155, v155
	v_add_f32_e32 v130, v151, v130
	v_exp_f32_e32 v156, v156
	v_add_f32_e32 v130, v152, v130
	v_exp_f32_e32 v157, v157
	v_add_f32_e32 v130, v153, v130
	v_exp_f32_e32 v158, v158
	v_add_f32_e32 v130, v154, v130
	v_exp_f32_e32 v159, v159
	v_add_f32_e32 v130, v155, v130
	v_exp_f32_e32 v160, v160
	v_add_f32_e32 v130, v156, v130
	v_exp_f32_e32 v161, v161
	v_add_f32_e32 v130, v157, v130
	v_add_f32_e32 v130, v158, v130
	v_exp_f32_e32 v197, v131
	v_add_f32_e32 v130, v159, v130
	v_exp_f32_e32 v198, v132
	v_add_f32_e32 v130, v160, v130
	v_exp_f32_e32 v199, v133
	v_add_f32_e32 v130, v161, v130
	v_exp_f32_e32 v200, v134
	v_add_f32_e32 v130, v196, v130
	v_exp_f32_e32 v201, v135
	v_add_f32_e32 v130, v197, v130
	v_exp_f32_e32 v202, v136
	v_add_f32_e32 v130, v198, v130
	v_exp_f32_e32 v203, v137
	v_add_f32_e32 v130, v199, v130
	v_exp_f32_e32 v204, v138
	v_add_f32_e32 v130, v200, v130
	v_exp_f32_e32 v205, v139
	v_add_f32_e32 v130, v201, v130
	v_exp_f32_e32 v206, v140
	v_add_f32_e32 v130, v202, v130
	v_exp_f32_e32 v207, v141
	v_add_f32_e32 v130, v203, v130
	v_exp_f32_e32 v208, v142
	v_add_f32_e32 v130, v204, v130
	v_exp_f32_e32 v209, v143
	v_add_f32_e32 v130, v205, v130
	v_exp_f32_e32 v251, v144
	v_add_f32_e32 v130, v206, v130
	v_exp_f32_e32 v194, v194
	v_add_f32_e32 v130, v207, v130
	v_add_f32_e32 v130, v208, v130
	v_add_f32_e32 v130, v209, v130
	v_add_f32_e32 v130, v251, v130
	v_add_f32_e32 v146, v194, v130
	v_mov_b32_e32 v147, v146
	s_nop 1
	v_permlane32_swap_b32_e32 v146, v147
	v_cvt_pk_bf16_f32 v130, v145, v195
	v_cvt_pk_bf16_f32 v131, v148, v149
	v_cvt_pk_bf16_f32 v132, v150, v151
	v_cvt_pk_bf16_f32 v133, v152, v153
	v_cvt_pk_bf16_f32 v134, v154, v155
	v_cvt_pk_bf16_f32 v135, v156, v157
	v_cvt_pk_bf16_f32 v136, v158, v159
	v_cvt_pk_bf16_f32 v137, v160, v161
	v_cvt_pk_bf16_f32 v138, v196, v197
	v_cvt_pk_bf16_f32 v139, v198, v199
	v_cvt_pk_bf16_f32 v140, v200, v201
	v_cvt_pk_bf16_f32 v141, v202, v203
	v_cvt_pk_bf16_f32 v142, v204, v205
	v_cvt_pk_bf16_f32 v143, v206, v207
	v_cvt_pk_bf16_f32 v144, v208, v209
	v_cvt_pk_bf16_f32 v145, v251, v194
	s_nop 0
	v_permlane32_swap_b32_e32 v130, v132
	v_permlane32_swap_b32_e32 v131, v133
	v_permlane32_swap_b32_e32 v134, v136
	v_permlane32_swap_b32_e32 v135, v137
	v_permlane32_swap_b32_e32 v138, v140
	v_permlane32_swap_b32_e32 v139, v141
	v_permlane32_swap_b32_e32 v142, v144
	v_permlane32_swap_b32_e32 v143, v145
	ds_read_b64_tr_b16 v[148:149], v235 offset:0
	ds_read_b64_tr_b16 v[150:151], v235 offset:0x800
	ds_read_b64_tr_b16 v[152:153], v235 offset:0x1000
	ds_read_b64_tr_b16 v[154:155], v235 offset:0x1800
	ds_read_b64_tr_b16 v[156:157], v235 offset:0x2000
	ds_read_b64_tr_b16 v[158:159], v235 offset:0x2800
	ds_read_b64_tr_b16 v[194:195], v235 offset:0x3000
	ds_read_b64_tr_b16 v[196:197], v235 offset:0x3800
	s_waitcnt lgkmcnt(0)
	s_nop 0
	v_mfma_f32_32x32x16_bf16 v[2:17], v[130:133], v[148:151], v[2:17]
	ds_read_b64_tr_b16 v[148:149], v235 offset:0x200
	ds_read_b64_tr_b16 v[150:151], v235 offset:0xa00
	v_mfma_f32_32x32x16_bf16 v[2:17], v[134:137], v[152:155], v[2:17]
	ds_read_b64_tr_b16 v[152:153], v235 offset:0x1200
	ds_read_b64_tr_b16 v[154:155], v235 offset:0x1a00
	v_mfma_f32_32x32x16_bf16 v[2:17], v[138:141], v[156:159], v[2:17]
	ds_read_b64_tr_b16 v[156:157], v235 offset:0x2200
	ds_read_b64_tr_b16 v[158:159], v235 offset:0x2a00
	v_mfma_f32_32x32x16_bf16 v[2:17], v[142:145], v[194:197], v[2:17]
	ds_read_b64_tr_b16 v[194:195], v235 offset:0x3200
	ds_read_b64_tr_b16 v[196:197], v235 offset:0x3a00
	s_waitcnt lgkmcnt(0)
	v_mfma_f32_32x32x16_bf16 v[18:33], v[130:133], v[148:151], v[18:33]
	ds_read_b64_tr_b16 v[148:149], v235 offset:0x400
	ds_read_b64_tr_b16 v[150:151], v235 offset:0xc00
	v_mfma_f32_32x32x16_bf16 v[18:33], v[134:137], v[152:155], v[18:33]
	ds_read_b64_tr_b16 v[152:153], v235 offset:0x1400
	ds_read_b64_tr_b16 v[154:155], v235 offset:0x1c00
	v_mfma_f32_32x32x16_bf16 v[18:33], v[138:141], v[156:159], v[18:33]
	ds_read_b64_tr_b16 v[156:157], v235 offset:0x2400
	ds_read_b64_tr_b16 v[158:159], v235 offset:0x2c00
	v_mfma_f32_32x32x16_bf16 v[18:33], v[142:145], v[194:197], v[18:33]
	ds_read_b64_tr_b16 v[194:195], v235 offset:0x3400
	ds_read_b64_tr_b16 v[196:197], v235 offset:0x3c00
	s_waitcnt lgkmcnt(0)
	v_mfma_f32_32x32x16_bf16 v[34:49], v[130:133], v[148:151], v[34:49]
	ds_read_b64_tr_b16 v[148:149], v235 offset:0x600
	ds_read_b64_tr_b16 v[150:151], v235 offset:0xe00
	v_mfma_f32_32x32x16_bf16 v[34:49], v[134:137], v[152:155], v[34:49]
	ds_read_b64_tr_b16 v[152:153], v235 offset:0x1600
	ds_read_b64_tr_b16 v[154:155], v235 offset:0x1e00
	v_mfma_f32_32x32x16_bf16 v[34:49], v[138:141], v[156:159], v[34:49]
	ds_read_b64_tr_b16 v[156:157], v235 offset:0x2600
	ds_read_b64_tr_b16 v[158:159], v235 offset:0x2e00
	v_mfma_f32_32x32x16_bf16 v[34:49], v[142:145], v[194:197], v[34:49]
	ds_read_b64_tr_b16 v[194:195], v235 offset:0x3600
	ds_read_b64_tr_b16 v[196:197], v235 offset:0x3e00
	s_waitcnt lgkmcnt(0)
	v_mfma_f32_32x32x16_bf16 v[50:65], v[130:133], v[148:151], v[50:65]
	ds_read_b64_tr_b16 v[148:149], v236 offset:0
	ds_read_b64_tr_b16 v[150:151], v236 offset:0x800
	v_mfma_f32_32x32x16_bf16 v[50:65], v[134:137], v[152:155], v[50:65]
	ds_read_b64_tr_b16 v[152:153], v236 offset:0x1000
	ds_read_b64_tr_b16 v[154:155], v236 offset:0x1800
	v_mfma_f32_32x32x16_bf16 v[50:65], v[138:141], v[156:159], v[50:65]
	ds_read_b64_tr_b16 v[156:157], v236 offset:0x2000
	ds_read_b64_tr_b16 v[158:159], v236 offset:0x2800
	v_mfma_f32_32x32x16_bf16 v[50:65], v[142:145], v[194:197], v[50:65]
	ds_read_b64_tr_b16 v[194:195], v236 offset:0x3000
	ds_read_b64_tr_b16 v[196:197], v236 offset:0x3800
	s_waitcnt lgkmcnt(0)
	v_mfma_f32_32x32x16_bf16 v[66:81], v[130:133], v[148:151], v[66:81]
	ds_read_b64_tr_b16 v[148:149], v236 offset:0x200
	ds_read_b64_tr_b16 v[150:151], v236 offset:0xa00
	v_mfma_f32_32x32x16_bf16 v[66:81], v[134:137], v[152:155], v[66:81]
	ds_read_b64_tr_b16 v[152:153], v236 offset:0x1200
	ds_read_b64_tr_b16 v[154:155], v236 offset:0x1a00
	v_mfma_f32_32x32x16_bf16 v[66:81], v[138:141], v[156:159], v[66:81]
	ds_read_b64_tr_b16 v[156:157], v236 offset:0x2200
	ds_read_b64_tr_b16 v[158:159], v236 offset:0x2a00
	v_mfma_f32_32x32x16_bf16 v[66:81], v[142:145], v[194:197], v[66:81]
	ds_read_b64_tr_b16 v[194:195], v236 offset:0x3200
	ds_read_b64_tr_b16 v[196:197], v236 offset:0x3a00
	s_waitcnt lgkmcnt(0)
	v_mfma_f32_32x32x16_bf16 v[82:97], v[130:133], v[148:151], v[82:97]
	ds_read_b64_tr_b16 v[148:149], v236 offset:0x400
	ds_read_b64_tr_b16 v[150:151], v236 offset:0xc00
	v_mfma_f32_32x32x16_bf16 v[82:97], v[134:137], v[152:155], v[82:97]
	ds_read_b64_tr_b16 v[152:153], v236 offset:0x1400
	ds_read_b64_tr_b16 v[154:155], v236 offset:0x1c00
	v_mfma_f32_32x32x16_bf16 v[82:97], v[138:141], v[156:159], v[82:97]
	ds_read_b64_tr_b16 v[156:157], v236 offset:0x2400
	ds_read_b64_tr_b16 v[158:159], v236 offset:0x2c00
	v_mfma_f32_32x32x16_bf16 v[82:97], v[142:145], v[194:197], v[82:97]
	ds_read_b64_tr_b16 v[194:195], v236 offset:0x3400
	ds_read_b64_tr_b16 v[196:197], v236 offset:0x3c00
	s_waitcnt lgkmcnt(0)
	v_mfma_f32_32x32x16_bf16 v[98:113], v[130:133], v[148:151], v[98:113]
	ds_read_b64_tr_b16 v[148:149], v236 offset:0x600
	ds_read_b64_tr_b16 v[150:151], v236 offset:0xe00
	v_mfma_f32_32x32x16_bf16 v[98:113], v[134:137], v[152:155], v[98:113]
	ds_read_b64_tr_b16 v[152:153], v236 offset:0x1600
	ds_read_b64_tr_b16 v[154:155], v236 offset:0x1e00
	v_mfma_f32_32x32x16_bf16 v[98:113], v[138:141], v[156:159], v[98:113]
	ds_read_b64_tr_b16 v[156:157], v236 offset:0x2600
	ds_read_b64_tr_b16 v[158:159], v236 offset:0x2e00
	v_mfma_f32_32x32x16_bf16 v[98:113], v[142:145], v[194:197], v[98:113]
	ds_read_b64_tr_b16 v[194:195], v236 offset:0x3600
	ds_read_b64_tr_b16 v[196:197], v236 offset:0x3e00
	s_waitcnt lgkmcnt(0)
	v_mfma_f32_32x32x16_bf16 v[114:129], v[130:133], v[148:151], v[114:129]
	s_barrier
	v_mfma_f32_32x32x16_bf16 v[114:129], v[134:137], v[152:155], v[114:129]
	v_mfma_f32_32x32x16_bf16 v[114:129], v[138:141], v[156:159], v[114:129]
	v_mfma_f32_32x32x16_bf16 v[114:129], v[142:145], v[194:197], v[114:129]
	s_mov_b64 s[80:81], 0xc0100
	s_mov_b64 s[82:83], 0xe0100
	s_branch .LBB0_584

	.amdhsa_kernel _Z6mk_fwd4Args
		.amdhsa_group_segment_fixed_size 0
		.amdhsa_private_segment_fixed_size 0
		.amdhsa_kernarg_size 480
		.amdhsa_user_sgpr_count 2
		.amdhsa_user_sgpr_dispatch_ptr 0
		.amdhsa_user_sgpr_queue_ptr 0
		.amdhsa_user_sgpr_kernarg_segment_ptr 1
		.amdhsa_user_sgpr_dispatch_id 0
		.amdhsa_user_sgpr_kernarg_preload_length 0
		.amdhsa_user_sgpr_kernarg_preload_offset 0
		.amdhsa_user_sgpr_private_segment_size 0
		.amdhsa_uses_dynamic_stack 0
		.amdhsa_enable_private_segment 0
		.amdhsa_system_sgpr_workgroup_id_x 1
		.amdhsa_system_sgpr_workgroup_id_y 0
		.amdhsa_system_sgpr_workgroup_id_z 0
		.amdhsa_system_sgpr_workgroup_info 0
		.amdhsa_system_vgpr_workitem_id 0
		.amdhsa_next_free_vgpr 255
		.amdhsa_next_free_sgpr 102
		.amdhsa_accum_offset 256
		.amdhsa_reserve_vcc 1
		.amdhsa_float_round_mode_32 0
		.amdhsa_float_round_mode_16_64 0
		.amdhsa_float_denorm_mode_32 3
		.amdhsa_float_denorm_mode_16_64 3
		.amdhsa_dx10_clamp 1
		.amdhsa_ieee_mode 1
		.amdhsa_fp16_overflow 0
		.amdhsa_tg_split 0
		.amdhsa_exception_fp_ieee_invalid_op 0
		.amdhsa_exception_fp_denorm_src 0
		.amdhsa_exception_fp_ieee_div_zero 0
		.amdhsa_exception_fp_ieee_overflow 0
		.amdhsa_exception_fp_ieee_underflow 0
		.amdhsa_exception_fp_ieee_inexact 0
		.amdhsa_exception_int_div_zero 0
	.end_amdhsa_kernel

amdhsa.kernels:
  - .agpr_count:     0
    .args:
      - .offset:         0
        .size:           224
        .value_kind:     by_value
      - .offset:         224
        .size:           4
        .value_kind:     hidden_block_count_x
      - .offset:         228
        .size:           4
        .value_kind:     hidden_block_count_y
      - .offset:         232
        .size:           4
        .value_kind:     hidden_block_count_z
      - .offset:         236
        .size:           2
        .value_kind:     hidden_group_size_x
      - .offset:         238
        .size:           2
        .value_kind:     hidden_group_size_y
      - .offset:         240
        .size:           2
        .value_kind:     hidden_group_size_z
      - .offset:         242
        .size:           2
        .value_kind:     hidden_remainder_x
      - .offset:         244
        .size:           2
        .value_kind:     hidden_remainder_y
      - .offset:         246
        .size:           2
        .value_kind:     hidden_remainder_z
      - .offset:         264
        .size:           8
        .value_kind:     hidden_global_offset_x
      - .offset:         272
        .size:           8
        .value_kind:     hidden_global_offset_y
      - .offset:         280
        .size:           8
        .value_kind:     hidden_global_offset_z
      - .offset:         288
        .size:           2
        .value_kind:     hidden_grid_dims
      - .offset:         344
        .size:           4
        .value_kind:     hidden_dynamic_lds_size
    .group_segment_fixed_size: 0
    .kernarg_segment_align: 8
    .kernarg_segment_size: 480
    .language:       OpenCL C
    .language_version:
      - 2
      - 0
    .max_flat_workgroup_size: 512
    .name:           _Z6mk_fwd4Args
    .private_segment_fixed_size: 0
    .sgpr_count:     108
    .sgpr_spill_count: 80
    .symbol:         _Z6mk_fwd4Args.kd
    .uniform_work_group_size: 1
    .uses_dynamic_stack: false
    .vgpr_count:     255
    .vgpr_spill_count: 0
    .wavefront_size: 64
